# deferred conversions now use a 4-deep load pipeline (more bytes in flight per CU)
# baseline (speedup 1.0000x reference)
.Ldw_begin:
	s_and_b32 s43, s2, 7
	s_lshl_b32 s31, s0, 3
	s_add_i32 s43, s43, s31
	s_lshl_b32 s43, s43, 3
	s_add_i32 s43, s43, s85
	v_lshrrev_b32_e32 v2, 3, v244
	v_and_b32_e32 v3, 7, v244
	v_lshlrev_b32_e32 v4, 13, v2
	v_lshl_add_u32 v4, v3, 4, v4
	s_lshl_b32 s31, s85, 14
	v_lshlrev_b32_e32 v5, 7, v2
	v_add_u32_e32 v5, s31, v5
	v_xor_b32_e32 v6, 0, v3
	v_lshl_add_u32 v110, v6, 4, v5
	v_xor_b32_e32 v6, 1, v3
	v_lshl_add_u32 v111, v6, 4, v5
	v_xor_b32_e32 v6, 2, v3
	v_lshl_add_u32 v112, v6, 4, v5
	v_xor_b32_e32 v6, 3, v3
	v_lshl_add_u32 v113, v6, 4, v5
	v_xor_b32_e32 v6, 4, v3
	v_lshl_add_u32 v114, v6, 4, v5
	v_xor_b32_e32 v6, 5, v3
	v_lshl_add_u32 v115, v6, 4, v5
	v_xor_b32_e32 v6, 6, v3
	v_lshl_add_u32 v116, v6, 4, v5
	v_xor_b32_e32 v6, 7, v3
	v_lshl_add_u32 v117, v6, 4, v5
	v_lshlrev_b32_e32 v7, 10, v3
	v_add_u32_e32 v7, s31, v7
	v_add_u32_e32 v8, 0, v2
	v_lshrrev_b32_e32 v9, 2, v8
	v_xor_b32_e32 v9, v9, v3
	v_and_b32_e32 v8, 3, v8
	v_lshl_add_u32 v8, v9, 2, v8
	v_lshl_add_u32 v118, v8, 2, v7
	v_add_u32_e32 v8, 8, v2
	v_lshrrev_b32_e32 v9, 2, v8
	v_xor_b32_e32 v9, v9, v3
	v_and_b32_e32 v8, 3, v8
	v_lshl_add_u32 v8, v9, 2, v8
	v_lshl_add_u32 v119, v8, 2, v7
	v_add_u32_e32 v8, 16, v2
	v_lshrrev_b32_e32 v9, 2, v8
	v_xor_b32_e32 v9, v9, v3
	v_and_b32_e32 v8, 3, v8
	v_lshl_add_u32 v8, v9, 2, v8
	v_lshl_add_u32 v120, v8, 2, v7
	v_add_u32_e32 v8, 24, v2
	v_lshrrev_b32_e32 v9, 2, v8
	v_xor_b32_e32 v9, v9, v3
	v_and_b32_e32 v8, 3, v8
	v_lshl_add_u32 v8, v9, 2, v8
	v_lshl_add_u32 v121, v8, 2, v7
	s_load_dwordx2 s[26:27], s[86:87], 0xd8
	s_load_dwordx2 s[28:29], s[86:87], 0x118
	s_mov_b32 s30, s43
	v_lshlrev_b32_e32 v74, 14, v2
	v_lshl_add_u32 v74, v3, 4, v74
	v_add_u32_e32 v75, 0x20000, v74
	v_add_u32_e32 v76, 0x40000, v74
	v_add_u32_e32 v77, 0x60000, v74
	s_waitcnt lgkmcnt(0)
	s_add_u32 s26, s26, 0x4000000
	s_addc_u32 s27, s27, 0
	s_add_u32 s28, s28, 0x8f00000
	s_addc_u32 s29, s29, 0
	s_lshr_b32 s34, s30, 6
	s_and_b32 s35, s30, 63
	s_mov_b32 s40, s30
	s_lshl_b32 s36, s34, 19
	s_lshl_b32 s37, s35, 7
	s_add_i32 s36, s36, s37
	s_add_u32 s38, s26, s36
	s_addc_u32 s39, s27, 0
	global_load_dwordx4 v[10:13], v4, s[38:39] nt
	s_add_u32 s38, s38, 0x10000
	s_addc_u32 s39, s39, 0
	global_load_dwordx4 v[14:17], v4, s[38:39] nt
	s_add_u32 s38, s38, 0x10000
	s_addc_u32 s39, s39, 0
	global_load_dwordx4 v[18:21], v4, s[38:39] nt
	s_add_u32 s38, s38, 0x10000
	s_addc_u32 s39, s39, 0
	global_load_dwordx4 v[22:25], v4, s[38:39] nt
	s_add_u32 s38, s38, 0x10000
	s_addc_u32 s39, s39, 0
	global_load_dwordx4 v[26:29], v4, s[38:39] nt
	s_add_u32 s38, s38, 0x10000
	s_addc_u32 s39, s39, 0
	global_load_dwordx4 v[30:33], v4, s[38:39] nt
	s_add_u32 s38, s38, 0x10000
	s_addc_u32 s39, s39, 0
	global_load_dwordx4 v[34:37], v4, s[38:39] nt
	s_add_u32 s38, s38, 0x10000
	s_addc_u32 s39, s39, 0
	global_load_dwordx4 v[38:41], v4, s[38:39] nt
	s_addk_i32 s30, 0x180
	s_and_b32 s30, s30, 0x1fff
	s_lshr_b32 s34, s30, 6
	s_and_b32 s35, s30, 63
	s_mov_b32 s41, s30
	s_lshl_b32 s36, s34, 19
	s_lshl_b32 s37, s35, 7
	s_add_i32 s36, s36, s37
	s_add_u32 s38, s26, s36
	s_addc_u32 s39, s27, 0
	global_load_dwordx4 v[42:45], v4, s[38:39] nt
	s_add_u32 s38, s38, 0x10000
	s_addc_u32 s39, s39, 0
	global_load_dwordx4 v[46:49], v4, s[38:39] nt
	s_add_u32 s38, s38, 0x10000
	s_addc_u32 s39, s39, 0
	global_load_dwordx4 v[50:53], v4, s[38:39] nt
	s_add_u32 s38, s38, 0x10000
	s_addc_u32 s39, s39, 0
	global_load_dwordx4 v[54:57], v4, s[38:39] nt
	s_add_u32 s38, s38, 0x10000
	s_addc_u32 s39, s39, 0
	global_load_dwordx4 v[58:61], v4, s[38:39] nt
	s_add_u32 s38, s38, 0x10000
	s_addc_u32 s39, s39, 0
	global_load_dwordx4 v[62:65], v4, s[38:39] nt
	s_add_u32 s38, s38, 0x10000
	s_addc_u32 s39, s39, 0
	global_load_dwordx4 v[66:69], v4, s[38:39] nt
	s_add_u32 s38, s38, 0x10000
	s_addc_u32 s39, s39, 0
	global_load_dwordx4 v[70:73], v4, s[38:39] nt
	s_addk_i32 s30, 0x180
	s_and_b32 s30, s30, 0x1fff
	s_lshr_b32 s34, s30, 6
	s_and_b32 s35, s30, 63
	s_mov_b32 s44, s30
	s_lshl_b32 s36, s34, 19
	s_lshl_b32 s37, s35, 7
	s_add_i32 s36, s36, s37
	s_add_u32 s38, s26, s36
	s_addc_u32 s39, s27, 0
	global_load_dwordx4 v[126:129], v4, s[38:39] nt
	s_add_u32 s38, s38, 0x10000
	s_addc_u32 s39, s39, 0
	global_load_dwordx4 v[130:133], v4, s[38:39] nt
	s_add_u32 s38, s38, 0x10000
	s_addc_u32 s39, s39, 0
	global_load_dwordx4 v[134:137], v4, s[38:39] nt
	s_add_u32 s38, s38, 0x10000
	s_addc_u32 s39, s39, 0
	global_load_dwordx4 v[138:141], v4, s[38:39] nt
	s_add_u32 s38, s38, 0x10000
	s_addc_u32 s39, s39, 0
	global_load_dwordx4 v[142:145], v4, s[38:39] nt
	s_add_u32 s38, s38, 0x10000
	s_addc_u32 s39, s39, 0
	global_load_dwordx4 v[146:149], v4, s[38:39] nt
	s_add_u32 s38, s38, 0x10000
	s_addc_u32 s39, s39, 0
	global_load_dwordx4 v[150:153], v4, s[38:39] nt
	s_add_u32 s38, s38, 0x10000
	s_addc_u32 s39, s39, 0
	global_load_dwordx4 v[154:157], v4, s[38:39] nt
	s_addk_i32 s30, 0x180
	s_and_b32 s30, s30, 0x1fff
	s_lshr_b32 s34, s30, 6
	s_and_b32 s35, s30, 63
	s_mov_b32 s45, s30
	s_lshl_b32 s36, s34, 19
	s_lshl_b32 s37, s35, 7
	s_add_i32 s36, s36, s37
	s_add_u32 s38, s26, s36
	s_addc_u32 s39, s27, 0
	global_load_dwordx4 v[158:161], v4, s[38:39] nt
	s_add_u32 s38, s38, 0x10000
	s_addc_u32 s39, s39, 0
	global_load_dwordx4 v[162:165], v4, s[38:39] nt
	s_add_u32 s38, s38, 0x10000
	s_addc_u32 s39, s39, 0
	global_load_dwordx4 v[166:169], v4, s[38:39] nt
	s_add_u32 s38, s38, 0x10000
	s_addc_u32 s39, s39, 0
	global_load_dwordx4 v[170:173], v4, s[38:39] nt
	s_add_u32 s38, s38, 0x10000
	s_addc_u32 s39, s39, 0
	global_load_dwordx4 v[174:177], v4, s[38:39] nt
	s_add_u32 s38, s38, 0x10000
	s_addc_u32 s39, s39, 0
	global_load_dwordx4 v[178:181], v4, s[38:39] nt
	s_add_u32 s38, s38, 0x10000
	s_addc_u32 s39, s39, 0
	global_load_dwordx4 v[182:185], v4, s[38:39] nt
	s_add_u32 s38, s38, 0x10000
	s_addc_u32 s39, s39, 0
	global_load_dwordx4 v[186:189], v4, s[38:39] nt
	s_addk_i32 s30, 0x180
	s_and_b32 s30, s30, 0x1fff
	s_waitcnt vmcnt(24)
	ds_write_b128 v110, v[10:13]
	ds_write_b128 v111, v[14:17] offset:1024
	ds_write_b128 v112, v[18:21] offset:2048
	ds_write_b128 v113, v[22:25] offset:3072
	ds_write_b128 v114, v[26:29] offset:4096
	ds_write_b128 v115, v[30:33] offset:5120
	ds_write_b128 v116, v[34:37] offset:6144
	ds_write_b128 v117, v[38:41] offset:7168
	ds_read2_b32 v[10:11], v118 offset1:32
	ds_read2_b32 v[12:13], v118 offset0:64 offset1:96
	ds_read2_b32 v[14:15], v118 offset0:128 offset1:160
	ds_read2_b32 v[16:17], v118 offset0:192 offset1:224
	ds_read2_b32 v[18:19], v119 offset1:32
	ds_read2_b32 v[20:21], v119 offset0:64 offset1:96
	ds_read2_b32 v[22:23], v119 offset0:128 offset1:160
	ds_read2_b32 v[24:25], v119 offset0:192 offset1:224
	ds_read2_b32 v[26:27], v120 offset1:32
	ds_read2_b32 v[28:29], v120 offset0:64 offset1:96
	ds_read2_b32 v[30:31], v120 offset0:128 offset1:160
	ds_read2_b32 v[32:33], v120 offset0:192 offset1:224
	ds_read2_b32 v[34:35], v121 offset1:32
	ds_read2_b32 v[36:37], v121 offset0:64 offset1:96
	ds_read2_b32 v[38:39], v121 offset0:128 offset1:160
	ds_read2_b32 v[40:41], v121 offset0:192 offset1:224
	s_lshr_b32 s34, s40, 6
	s_and_b32 s35, s40, 63
	s_lshl_b32 s36, s35, 19
	s_lshl_b32 s37, s34, 7
	s_add_i32 s36, s36, s37
	s_add_u32 s38, s28, s36
	s_addc_u32 s39, s29, 0
	s_waitcnt lgkmcnt(12)
	v_cvt_pk_bf16_f32 v78, v10, v11
	v_cvt_pk_bf16_f32 v79, v12, v13
	v_cvt_pk_bf16_f32 v80, v14, v15
	v_cvt_pk_bf16_f32 v81, v16, v17
	s_waitcnt lgkmcnt(8)
	v_cvt_pk_bf16_f32 v82, v18, v19
	v_cvt_pk_bf16_f32 v83, v20, v21
	v_cvt_pk_bf16_f32 v84, v22, v23
	v_cvt_pk_bf16_f32 v85, v24, v25
	s_waitcnt lgkmcnt(4)
	v_cvt_pk_bf16_f32 v86, v26, v27
	v_cvt_pk_bf16_f32 v87, v28, v29
	v_cvt_pk_bf16_f32 v88, v30, v31
	v_cvt_pk_bf16_f32 v89, v32, v33
	s_waitcnt lgkmcnt(0)
	v_cvt_pk_bf16_f32 v90, v34, v35
	v_cvt_pk_bf16_f32 v91, v36, v37
	v_cvt_pk_bf16_f32 v92, v38, v39
	v_cvt_pk_bf16_f32 v93, v40, v41
	global_store_dwordx4 v74, v[78:81], s[38:39]
	global_store_dwordx4 v75, v[82:85], s[38:39]
	global_store_dwordx4 v76, v[86:89], s[38:39]
	global_store_dwordx4 v77, v[90:93], s[38:39]
	s_lshr_b32 s34, s30, 6
	s_and_b32 s35, s30, 63
	s_mov_b32 s40, s30
	s_lshl_b32 s36, s34, 19
	s_lshl_b32 s37, s35, 7
	s_add_i32 s36, s36, s37
	s_add_u32 s38, s26, s36
	s_addc_u32 s39, s27, 0
	global_load_dwordx4 v[10:13], v4, s[38:39] nt
	s_add_u32 s38, s38, 0x10000
	s_addc_u32 s39, s39, 0
	global_load_dwordx4 v[14:17], v4, s[38:39] nt
	s_add_u32 s38, s38, 0x10000
	s_addc_u32 s39, s39, 0
	global_load_dwordx4 v[18:21], v4, s[38:39] nt
	s_add_u32 s38, s38, 0x10000
	s_addc_u32 s39, s39, 0
	global_load_dwordx4 v[22:25], v4, s[38:39] nt
	s_add_u32 s38, s38, 0x10000
	s_addc_u32 s39, s39, 0
	global_load_dwordx4 v[26:29], v4, s[38:39] nt
	s_add_u32 s38, s38, 0x10000
	s_addc_u32 s39, s39, 0
	global_load_dwordx4 v[30:33], v4, s[38:39] nt
	s_add_u32 s38, s38, 0x10000
	s_addc_u32 s39, s39, 0
	global_load_dwordx4 v[34:37], v4, s[38:39] nt
	s_add_u32 s38, s38, 0x10000
	s_addc_u32 s39, s39, 0
	global_load_dwordx4 v[38:41], v4, s[38:39] nt
	s_addk_i32 s30, 0x180
	s_and_b32 s30, s30, 0x1fff
	s_waitcnt vmcnt(28)
	ds_write_b128 v110, v[42:45]
	ds_write_b128 v111, v[46:49] offset:1024
	ds_write_b128 v112, v[50:53] offset:2048
	ds_write_b128 v113, v[54:57] offset:3072
	ds_write_b128 v114, v[58:61] offset:4096
	ds_write_b128 v115, v[62:65] offset:5120
	ds_write_b128 v116, v[66:69] offset:6144
	ds_write_b128 v117, v[70:73] offset:7168
	ds_read2_b32 v[42:43], v118 offset1:32
	ds_read2_b32 v[44:45], v118 offset0:64 offset1:96
	ds_read2_b32 v[46:47], v118 offset0:128 offset1:160
	ds_read2_b32 v[48:49], v118 offset0:192 offset1:224
	ds_read2_b32 v[50:51], v119 offset1:32
	ds_read2_b32 v[52:53], v119 offset0:64 offset1:96
	ds_read2_b32 v[54:55], v119 offset0:128 offset1:160
	ds_read2_b32 v[56:57], v119 offset0:192 offset1:224
	ds_read2_b32 v[58:59], v120 offset1:32
	ds_read2_b32 v[60:61], v120 offset0:64 offset1:96
	ds_read2_b32 v[62:63], v120 offset0:128 offset1:160
	ds_read2_b32 v[64:65], v120 offset0:192 offset1:224
	ds_read2_b32 v[66:67], v121 offset1:32
	ds_read2_b32 v[68:69], v121 offset0:64 offset1:96
	ds_read2_b32 v[70:71], v121 offset0:128 offset1:160
	ds_read2_b32 v[72:73], v121 offset0:192 offset1:224
	s_lshr_b32 s34, s41, 6
	s_and_b32 s35, s41, 63
	s_lshl_b32 s36, s35, 19
	s_lshl_b32 s37, s34, 7
	s_add_i32 s36, s36, s37
	s_add_u32 s38, s28, s36
	s_addc_u32 s39, s29, 0
	s_waitcnt lgkmcnt(12)
	v_cvt_pk_bf16_f32 v94, v42, v43
	v_cvt_pk_bf16_f32 v95, v44, v45
	v_cvt_pk_bf16_f32 v96, v46, v47
	v_cvt_pk_bf16_f32 v97, v48, v49
	s_waitcnt lgkmcnt(8)
	v_cvt_pk_bf16_f32 v98, v50, v51
	v_cvt_pk_bf16_f32 v99, v52, v53
	v_cvt_pk_bf16_f32 v100, v54, v55
	v_cvt_pk_bf16_f32 v101, v56, v57
	s_waitcnt lgkmcnt(4)
	v_cvt_pk_bf16_f32 v102, v58, v59
	v_cvt_pk_bf16_f32 v103, v60, v61
	v_cvt_pk_bf16_f32 v104, v62, v63
	v_cvt_pk_bf16_f32 v105, v64, v65
	s_waitcnt lgkmcnt(0)
	v_cvt_pk_bf16_f32 v106, v66, v67
	v_cvt_pk_bf16_f32 v107, v68, v69
	v_cvt_pk_bf16_f32 v108, v70, v71
	v_cvt_pk_bf16_f32 v109, v72, v73
	global_store_dwordx4 v74, v[94:97], s[38:39]
	global_store_dwordx4 v75, v[98:101], s[38:39]
	global_store_dwordx4 v76, v[102:105], s[38:39]
	global_store_dwordx4 v77, v[106:109], s[38:39]
	s_lshr_b32 s34, s30, 6
	s_and_b32 s35, s30, 63
	s_mov_b32 s41, s30
	s_lshl_b32 s36, s34, 19
	s_lshl_b32 s37, s35, 7
	s_add_i32 s36, s36, s37
	s_add_u32 s38, s26, s36
	s_addc_u32 s39, s27, 0
	global_load_dwordx4 v[42:45], v4, s[38:39] nt
	s_add_u32 s38, s38, 0x10000
	s_addc_u32 s39, s39, 0
	global_load_dwordx4 v[46:49], v4, s[38:39] nt
	s_add_u32 s38, s38, 0x10000
	s_addc_u32 s39, s39, 0
	global_load_dwordx4 v[50:53], v4, s[38:39] nt
	s_add_u32 s38, s38, 0x10000
	s_addc_u32 s39, s39, 0
	global_load_dwordx4 v[54:57], v4, s[38:39] nt
	s_add_u32 s38, s38, 0x10000
	s_addc_u32 s39, s39, 0
	global_load_dwordx4 v[58:61], v4, s[38:39] nt
	s_add_u32 s38, s38, 0x10000
	s_addc_u32 s39, s39, 0
	global_load_dwordx4 v[62:65], v4, s[38:39] nt
	s_add_u32 s38, s38, 0x10000
	s_addc_u32 s39, s39, 0
	global_load_dwordx4 v[66:69], v4, s[38:39] nt
	s_add_u32 s38, s38, 0x10000
	s_addc_u32 s39, s39, 0
	global_load_dwordx4 v[70:73], v4, s[38:39] nt
	s_addk_i32 s30, 0x180
	s_and_b32 s30, s30, 0x1fff
	s_waitcnt vmcnt(32)
	ds_write_b128 v110, v[126:129]
	ds_write_b128 v111, v[130:133] offset:1024
	ds_write_b128 v112, v[134:137] offset:2048
	ds_write_b128 v113, v[138:141] offset:3072
	ds_write_b128 v114, v[142:145] offset:4096
	ds_write_b128 v115, v[146:149] offset:5120
	ds_write_b128 v116, v[150:153] offset:6144
	ds_write_b128 v117, v[154:157] offset:7168
	ds_read2_b32 v[126:127], v118 offset1:32
	ds_read2_b32 v[128:129], v118 offset0:64 offset1:96
	ds_read2_b32 v[130:131], v118 offset0:128 offset1:160
	ds_read2_b32 v[132:133], v118 offset0:192 offset1:224
	ds_read2_b32 v[134:135], v119 offset1:32
	ds_read2_b32 v[136:137], v119 offset0:64 offset1:96
	ds_read2_b32 v[138:139], v119 offset0:128 offset1:160
	ds_read2_b32 v[140:141], v119 offset0:192 offset1:224
	ds_read2_b32 v[142:143], v120 offset1:32
	ds_read2_b32 v[144:145], v120 offset0:64 offset1:96
	ds_read2_b32 v[146:147], v120 offset0:128 offset1:160
	ds_read2_b32 v[148:149], v120 offset0:192 offset1:224
	ds_read2_b32 v[150:151], v121 offset1:32
	ds_read2_b32 v[152:153], v121 offset0:64 offset1:96
	ds_read2_b32 v[154:155], v121 offset0:128 offset1:160
	ds_read2_b32 v[156:157], v121 offset0:192 offset1:224
	s_lshr_b32 s34, s44, 6
	s_and_b32 s35, s44, 63
	s_lshl_b32 s36, s35, 19
	s_lshl_b32 s37, s34, 7
	s_add_i32 s36, s36, s37
	s_add_u32 s38, s28, s36
	s_addc_u32 s39, s29, 0
	s_waitcnt lgkmcnt(12)
	v_cvt_pk_bf16_f32 v78, v126, v127
	v_cvt_pk_bf16_f32 v79, v128, v129
	v_cvt_pk_bf16_f32 v80, v130, v131
	v_cvt_pk_bf16_f32 v81, v132, v133
	s_waitcnt lgkmcnt(8)
	v_cvt_pk_bf16_f32 v82, v134, v135
	v_cvt_pk_bf16_f32 v83, v136, v137
	v_cvt_pk_bf16_f32 v84, v138, v139
	v_cvt_pk_bf16_f32 v85, v140, v141
	s_waitcnt lgkmcnt(4)
	v_cvt_pk_bf16_f32 v86, v142, v143
	v_cvt_pk_bf16_f32 v87, v144, v145
	v_cvt_pk_bf16_f32 v88, v146, v147
	v_cvt_pk_bf16_f32 v89, v148, v149
	s_waitcnt lgkmcnt(0)
	v_cvt_pk_bf16_f32 v90, v150, v151
	v_cvt_pk_bf16_f32 v91, v152, v153
	v_cvt_pk_bf16_f32 v92, v154, v155
	v_cvt_pk_bf16_f32 v93, v156, v157
	global_store_dwordx4 v74, v[78:81], s[38:39]
	global_store_dwordx4 v75, v[82:85], s[38:39]
	global_store_dwordx4 v76, v[86:89], s[38:39]
	global_store_dwordx4 v77, v[90:93], s[38:39]
	s_lshr_b32 s34, s30, 6
	s_and_b32 s35, s30, 63
	s_mov_b32 s44, s30
	s_lshl_b32 s36, s34, 19
	s_lshl_b32 s37, s35, 7
	s_add_i32 s36, s36, s37
	s_add_u32 s38, s26, s36
	s_addc_u32 s39, s27, 0
	global_load_dwordx4 v[126:129], v4, s[38:39] nt
	s_add_u32 s38, s38, 0x10000
	s_addc_u32 s39, s39, 0
	global_load_dwordx4 v[130:133], v4, s[38:39] nt
	s_add_u32 s38, s38, 0x10000
	s_addc_u32 s39, s39, 0
	global_load_dwordx4 v[134:137], v4, s[38:39] nt
	s_add_u32 s38, s38, 0x10000
	s_addc_u32 s39, s39, 0
	global_load_dwordx4 v[138:141], v4, s[38:39] nt
	s_add_u32 s38, s38, 0x10000
	s_addc_u32 s39, s39, 0
	global_load_dwordx4 v[142:145], v4, s[38:39] nt
	s_add_u32 s38, s38, 0x10000
	s_addc_u32 s39, s39, 0
	global_load_dwordx4 v[146:149], v4, s[38:39] nt
	s_add_u32 s38, s38, 0x10000
	s_addc_u32 s39, s39, 0
	global_load_dwordx4 v[150:153], v4, s[38:39] nt
	s_add_u32 s38, s38, 0x10000
	s_addc_u32 s39, s39, 0
	global_load_dwordx4 v[154:157], v4, s[38:39] nt
	s_addk_i32 s30, 0x180
	s_and_b32 s30, s30, 0x1fff
	s_waitcnt vmcnt(36)
	ds_write_b128 v110, v[158:161]
	ds_write_b128 v111, v[162:165] offset:1024
	ds_write_b128 v112, v[166:169] offset:2048
	ds_write_b128 v113, v[170:173] offset:3072
	ds_write_b128 v114, v[174:177] offset:4096
	ds_write_b128 v115, v[178:181] offset:5120
	ds_write_b128 v116, v[182:185] offset:6144
	ds_write_b128 v117, v[186:189] offset:7168
	ds_read2_b32 v[158:159], v118 offset1:32
	ds_read2_b32 v[160:161], v118 offset0:64 offset1:96
	ds_read2_b32 v[162:163], v118 offset0:128 offset1:160
	ds_read2_b32 v[164:165], v118 offset0:192 offset1:224
	ds_read2_b32 v[166:167], v119 offset1:32
	ds_read2_b32 v[168:169], v119 offset0:64 offset1:96
	ds_read2_b32 v[170:171], v119 offset0:128 offset1:160
	ds_read2_b32 v[172:173], v119 offset0:192 offset1:224
	ds_read2_b32 v[174:175], v120 offset1:32
	ds_read2_b32 v[176:177], v120 offset0:64 offset1:96
	ds_read2_b32 v[178:179], v120 offset0:128 offset1:160
	ds_read2_b32 v[180:181], v120 offset0:192 offset1:224
	ds_read2_b32 v[182:183], v121 offset1:32
	ds_read2_b32 v[184:185], v121 offset0:64 offset1:96
	ds_read2_b32 v[186:187], v121 offset0:128 offset1:160
	ds_read2_b32 v[188:189], v121 offset0:192 offset1:224
	s_lshr_b32 s34, s45, 6
	s_and_b32 s35, s45, 63
	s_lshl_b32 s36, s35, 19
	s_lshl_b32 s37, s34, 7
	s_add_i32 s36, s36, s37
	s_add_u32 s38, s28, s36
	s_addc_u32 s39, s29, 0
	s_waitcnt lgkmcnt(12)
	v_cvt_pk_bf16_f32 v94, v158, v159
	v_cvt_pk_bf16_f32 v95, v160, v161
	v_cvt_pk_bf16_f32 v96, v162, v163
	v_cvt_pk_bf16_f32 v97, v164, v165
	s_waitcnt lgkmcnt(8)
	v_cvt_pk_bf16_f32 v98, v166, v167
	v_cvt_pk_bf16_f32 v99, v168, v169
	v_cvt_pk_bf16_f32 v100, v170, v171
	v_cvt_pk_bf16_f32 v101, v172, v173
	s_waitcnt lgkmcnt(4)
	v_cvt_pk_bf16_f32 v102, v174, v175
	v_cvt_pk_bf16_f32 v103, v176, v177
	v_cvt_pk_bf16_f32 v104, v178, v179
	v_cvt_pk_bf16_f32 v105, v180, v181
	s_waitcnt lgkmcnt(0)
	v_cvt_pk_bf16_f32 v106, v182, v183
	v_cvt_pk_bf16_f32 v107, v184, v185
	v_cvt_pk_bf16_f32 v108, v186, v187
	v_cvt_pk_bf16_f32 v109, v188, v189
	global_store_dwordx4 v74, v[94:97], s[38:39]
	global_store_dwordx4 v75, v[98:101], s[38:39]
	global_store_dwordx4 v76, v[102:105], s[38:39]
	global_store_dwordx4 v77, v[106:109], s[38:39]
	s_lshr_b32 s34, s30, 6
	s_and_b32 s35, s30, 63
	s_mov_b32 s45, s30
	s_lshl_b32 s36, s34, 19
	s_lshl_b32 s37, s35, 7
	s_add_i32 s36, s36, s37
	s_add_u32 s38, s26, s36
	s_addc_u32 s39, s27, 0
	global_load_dwordx4 v[158:161], v4, s[38:39] nt
	s_add_u32 s38, s38, 0x10000
	s_addc_u32 s39, s39, 0
	global_load_dwordx4 v[162:165], v4, s[38:39] nt
	s_add_u32 s38, s38, 0x10000
	s_addc_u32 s39, s39, 0
	global_load_dwordx4 v[166:169], v4, s[38:39] nt
	s_add_u32 s38, s38, 0x10000
	s_addc_u32 s39, s39, 0
	global_load_dwordx4 v[170:173], v4, s[38:39] nt
	s_add_u32 s38, s38, 0x10000
	s_addc_u32 s39, s39, 0
	global_load_dwordx4 v[174:177], v4, s[38:39] nt
	s_add_u32 s38, s38, 0x10000
	s_addc_u32 s39, s39, 0
	global_load_dwordx4 v[178:181], v4, s[38:39] nt
	s_add_u32 s38, s38, 0x10000
	s_addc_u32 s39, s39, 0
	global_load_dwordx4 v[182:185], v4, s[38:39] nt
	s_add_u32 s38, s38, 0x10000
	s_addc_u32 s39, s39, 0
	global_load_dwordx4 v[186:189], v4, s[38:39] nt
	s_addk_i32 s30, 0x180
	s_and_b32 s30, s30, 0x1fff
	s_mov_b32 s42, 4
.Ldw_w2_loop:
	s_waitcnt vmcnt(36)
	ds_write_b128 v110, v[10:13]
	ds_write_b128 v111, v[14:17] offset:1024
	ds_write_b128 v112, v[18:21] offset:2048
	ds_write_b128 v113, v[22:25] offset:3072
	ds_write_b128 v114, v[26:29] offset:4096
	ds_write_b128 v115, v[30:33] offset:5120
	ds_write_b128 v116, v[34:37] offset:6144
	ds_write_b128 v117, v[38:41] offset:7168
	ds_read2_b32 v[10:11], v118 offset1:32
	ds_read2_b32 v[12:13], v118 offset0:64 offset1:96
	ds_read2_b32 v[14:15], v118 offset0:128 offset1:160
	ds_read2_b32 v[16:17], v118 offset0:192 offset1:224
	ds_read2_b32 v[18:19], v119 offset1:32
	ds_read2_b32 v[20:21], v119 offset0:64 offset1:96
	ds_read2_b32 v[22:23], v119 offset0:128 offset1:160
	ds_read2_b32 v[24:25], v119 offset0:192 offset1:224
	ds_read2_b32 v[26:27], v120 offset1:32
	ds_read2_b32 v[28:29], v120 offset0:64 offset1:96
	ds_read2_b32 v[30:31], v120 offset0:128 offset1:160
	ds_read2_b32 v[32:33], v120 offset0:192 offset1:224
	ds_read2_b32 v[34:35], v121 offset1:32
	ds_read2_b32 v[36:37], v121 offset0:64 offset1:96
	ds_read2_b32 v[38:39], v121 offset0:128 offset1:160
	ds_read2_b32 v[40:41], v121 offset0:192 offset1:224
	s_lshr_b32 s34, s40, 6
	s_and_b32 s35, s40, 63
	s_lshl_b32 s36, s35, 19
	s_lshl_b32 s37, s34, 7
	s_add_i32 s36, s36, s37
	s_add_u32 s38, s28, s36
	s_addc_u32 s39, s29, 0
	s_waitcnt lgkmcnt(12)
	v_cvt_pk_bf16_f32 v78, v10, v11
	v_cvt_pk_bf16_f32 v79, v12, v13
	v_cvt_pk_bf16_f32 v80, v14, v15
	v_cvt_pk_bf16_f32 v81, v16, v17
	s_waitcnt lgkmcnt(8)
	v_cvt_pk_bf16_f32 v82, v18, v19
	v_cvt_pk_bf16_f32 v83, v20, v21
	v_cvt_pk_bf16_f32 v84, v22, v23
	v_cvt_pk_bf16_f32 v85, v24, v25
	s_waitcnt lgkmcnt(4)
	v_cvt_pk_bf16_f32 v86, v26, v27
	v_cvt_pk_bf16_f32 v87, v28, v29
	v_cvt_pk_bf16_f32 v88, v30, v31
	v_cvt_pk_bf16_f32 v89, v32, v33
	s_waitcnt lgkmcnt(0)
	v_cvt_pk_bf16_f32 v90, v34, v35
	v_cvt_pk_bf16_f32 v91, v36, v37
	v_cvt_pk_bf16_f32 v92, v38, v39
	v_cvt_pk_bf16_f32 v93, v40, v41
	global_store_dwordx4 v74, v[78:81], s[38:39]
	global_store_dwordx4 v75, v[82:85], s[38:39]
	global_store_dwordx4 v76, v[86:89], s[38:39]
	global_store_dwordx4 v77, v[90:93], s[38:39]
	s_lshr_b32 s34, s30, 6
	s_and_b32 s35, s30, 63
	s_mov_b32 s40, s30
	s_lshl_b32 s36, s34, 19
	s_lshl_b32 s37, s35, 7
	s_add_i32 s36, s36, s37
	s_add_u32 s38, s26, s36
	s_addc_u32 s39, s27, 0
	global_load_dwordx4 v[10:13], v4, s[38:39] nt
	s_add_u32 s38, s38, 0x10000
	s_addc_u32 s39, s39, 0
	global_load_dwordx4 v[14:17], v4, s[38:39] nt
	s_add_u32 s38, s38, 0x10000
	s_addc_u32 s39, s39, 0
	global_load_dwordx4 v[18:21], v4, s[38:39] nt
	s_add_u32 s38, s38, 0x10000
	s_addc_u32 s39, s39, 0
	global_load_dwordx4 v[22:25], v4, s[38:39] nt
	s_add_u32 s38, s38, 0x10000
	s_addc_u32 s39, s39, 0
	global_load_dwordx4 v[26:29], v4, s[38:39] nt
	s_add_u32 s38, s38, 0x10000
	s_addc_u32 s39, s39, 0
	global_load_dwordx4 v[30:33], v4, s[38:39] nt
	s_add_u32 s38, s38, 0x10000
	s_addc_u32 s39, s39, 0
	global_load_dwordx4 v[34:37], v4, s[38:39] nt
	s_add_u32 s38, s38, 0x10000
	s_addc_u32 s39, s39, 0
	global_load_dwordx4 v[38:41], v4, s[38:39] nt
	s_addk_i32 s30, 0x180
	s_and_b32 s30, s30, 0x1fff
	s_waitcnt vmcnt(36)
	ds_write_b128 v110, v[42:45]
	ds_write_b128 v111, v[46:49] offset:1024
	ds_write_b128 v112, v[50:53] offset:2048
	ds_write_b128 v113, v[54:57] offset:3072
	ds_write_b128 v114, v[58:61] offset:4096
	ds_write_b128 v115, v[62:65] offset:5120
	ds_write_b128 v116, v[66:69] offset:6144
	ds_write_b128 v117, v[70:73] offset:7168
	ds_read2_b32 v[42:43], v118 offset1:32
	ds_read2_b32 v[44:45], v118 offset0:64 offset1:96
	ds_read2_b32 v[46:47], v118 offset0:128 offset1:160
	ds_read2_b32 v[48:49], v118 offset0:192 offset1:224
	ds_read2_b32 v[50:51], v119 offset1:32
	ds_read2_b32 v[52:53], v119 offset0:64 offset1:96
	ds_read2_b32 v[54:55], v119 offset0:128 offset1:160
	ds_read2_b32 v[56:57], v119 offset0:192 offset1:224
	ds_read2_b32 v[58:59], v120 offset1:32
	ds_read2_b32 v[60:61], v120 offset0:64 offset1:96
	ds_read2_b32 v[62:63], v120 offset0:128 offset1:160
	ds_read2_b32 v[64:65], v120 offset0:192 offset1:224
	ds_read2_b32 v[66:67], v121 offset1:32
	ds_read2_b32 v[68:69], v121 offset0:64 offset1:96
	ds_read2_b32 v[70:71], v121 offset0:128 offset1:160
	ds_read2_b32 v[72:73], v121 offset0:192 offset1:224
	s_lshr_b32 s34, s41, 6
	s_and_b32 s35, s41, 63
	s_lshl_b32 s36, s35, 19
	s_lshl_b32 s37, s34, 7
	s_add_i32 s36, s36, s37
	s_add_u32 s38, s28, s36
	s_addc_u32 s39, s29, 0
	s_waitcnt lgkmcnt(12)
	v_cvt_pk_bf16_f32 v94, v42, v43
	v_cvt_pk_bf16_f32 v95, v44, v45
	v_cvt_pk_bf16_f32 v96, v46, v47
	v_cvt_pk_bf16_f32 v97, v48, v49
	s_waitcnt lgkmcnt(8)
	v_cvt_pk_bf16_f32 v98, v50, v51
	v_cvt_pk_bf16_f32 v99, v52, v53
	v_cvt_pk_bf16_f32 v100, v54, v55
	v_cvt_pk_bf16_f32 v101, v56, v57
	s_waitcnt lgkmcnt(4)
	v_cvt_pk_bf16_f32 v102, v58, v59
	v_cvt_pk_bf16_f32 v103, v60, v61
	v_cvt_pk_bf16_f32 v104, v62, v63
	v_cvt_pk_bf16_f32 v105, v64, v65
	s_waitcnt lgkmcnt(0)
	v_cvt_pk_bf16_f32 v106, v66, v67
	v_cvt_pk_bf16_f32 v107, v68, v69
	v_cvt_pk_bf16_f32 v108, v70, v71
	v_cvt_pk_bf16_f32 v109, v72, v73
	global_store_dwordx4 v74, v[94:97], s[38:39]
	global_store_dwordx4 v75, v[98:101], s[38:39]
	global_store_dwordx4 v76, v[102:105], s[38:39]
	global_store_dwordx4 v77, v[106:109], s[38:39]
	s_lshr_b32 s34, s30, 6
	s_and_b32 s35, s30, 63
	s_mov_b32 s41, s30
	s_lshl_b32 s36, s34, 19
	s_lshl_b32 s37, s35, 7
	s_add_i32 s36, s36, s37
	s_add_u32 s38, s26, s36
	s_addc_u32 s39, s27, 0
	global_load_dwordx4 v[42:45], v4, s[38:39] nt
	s_add_u32 s38, s38, 0x10000
	s_addc_u32 s39, s39, 0
	global_load_dwordx4 v[46:49], v4, s[38:39] nt
	s_add_u32 s38, s38, 0x10000
	s_addc_u32 s39, s39, 0
	global_load_dwordx4 v[50:53], v4, s[38:39] nt
	s_add_u32 s38, s38, 0x10000
	s_addc_u32 s39, s39, 0
	global_load_dwordx4 v[54:57], v4, s[38:39] nt
	s_add_u32 s38, s38, 0x10000
	s_addc_u32 s39, s39, 0
	global_load_dwordx4 v[58:61], v4, s[38:39] nt
	s_add_u32 s38, s38, 0x10000
	s_addc_u32 s39, s39, 0
	global_load_dwordx4 v[62:65], v4, s[38:39] nt
	s_add_u32 s38, s38, 0x10000
	s_addc_u32 s39, s39, 0
	global_load_dwordx4 v[66:69], v4, s[38:39] nt
	s_add_u32 s38, s38, 0x10000
	s_addc_u32 s39, s39, 0
	global_load_dwordx4 v[70:73], v4, s[38:39] nt
	s_addk_i32 s30, 0x180
	s_and_b32 s30, s30, 0x1fff
	s_waitcnt vmcnt(36)
	ds_write_b128 v110, v[126:129]
	ds_write_b128 v111, v[130:133] offset:1024
	ds_write_b128 v112, v[134:137] offset:2048
	ds_write_b128 v113, v[138:141] offset:3072
	ds_write_b128 v114, v[142:145] offset:4096
	ds_write_b128 v115, v[146:149] offset:5120
	ds_write_b128 v116, v[150:153] offset:6144
	ds_write_b128 v117, v[154:157] offset:7168
	ds_read2_b32 v[126:127], v118 offset1:32
	ds_read2_b32 v[128:129], v118 offset0:64 offset1:96
	ds_read2_b32 v[130:131], v118 offset0:128 offset1:160
	ds_read2_b32 v[132:133], v118 offset0:192 offset1:224
	ds_read2_b32 v[134:135], v119 offset1:32
	ds_read2_b32 v[136:137], v119 offset0:64 offset1:96
	ds_read2_b32 v[138:139], v119 offset0:128 offset1:160
	ds_read2_b32 v[140:141], v119 offset0:192 offset1:224
	ds_read2_b32 v[142:143], v120 offset1:32
	ds_read2_b32 v[144:145], v120 offset0:64 offset1:96
	ds_read2_b32 v[146:147], v120 offset0:128 offset1:160
	ds_read2_b32 v[148:149], v120 offset0:192 offset1:224
	ds_read2_b32 v[150:151], v121 offset1:32
	ds_read2_b32 v[152:153], v121 offset0:64 offset1:96
	ds_read2_b32 v[154:155], v121 offset0:128 offset1:160
	ds_read2_b32 v[156:157], v121 offset0:192 offset1:224
	s_lshr_b32 s34, s44, 6
	s_and_b32 s35, s44, 63
	s_lshl_b32 s36, s35, 19
	s_lshl_b32 s37, s34, 7
	s_add_i32 s36, s36, s37
	s_add_u32 s38, s28, s36
	s_addc_u32 s39, s29, 0
	s_waitcnt lgkmcnt(12)
	v_cvt_pk_bf16_f32 v78, v126, v127
	v_cvt_pk_bf16_f32 v79, v128, v129
	v_cvt_pk_bf16_f32 v80, v130, v131
	v_cvt_pk_bf16_f32 v81, v132, v133
	s_waitcnt lgkmcnt(8)
	v_cvt_pk_bf16_f32 v82, v134, v135
	v_cvt_pk_bf16_f32 v83, v136, v137
	v_cvt_pk_bf16_f32 v84, v138, v139
	v_cvt_pk_bf16_f32 v85, v140, v141
	s_waitcnt lgkmcnt(4)
	v_cvt_pk_bf16_f32 v86, v142, v143
	v_cvt_pk_bf16_f32 v87, v144, v145
	v_cvt_pk_bf16_f32 v88, v146, v147
	v_cvt_pk_bf16_f32 v89, v148, v149
	s_waitcnt lgkmcnt(0)
	v_cvt_pk_bf16_f32 v90, v150, v151
	v_cvt_pk_bf16_f32 v91, v152, v153
	v_cvt_pk_bf16_f32 v92, v154, v155
	v_cvt_pk_bf16_f32 v93, v156, v157
	global_store_dwordx4 v74, v[78:81], s[38:39]
	global_store_dwordx4 v75, v[82:85], s[38:39]
	global_store_dwordx4 v76, v[86:89], s[38:39]
	global_store_dwordx4 v77, v[90:93], s[38:39]
	s_lshr_b32 s34, s30, 6
	s_and_b32 s35, s30, 63
	s_mov_b32 s44, s30
	s_lshl_b32 s36, s34, 19
	s_lshl_b32 s37, s35, 7
	s_add_i32 s36, s36, s37
	s_add_u32 s38, s26, s36
	s_addc_u32 s39, s27, 0
	global_load_dwordx4 v[126:129], v4, s[38:39] nt
	s_add_u32 s38, s38, 0x10000
	s_addc_u32 s39, s39, 0
	global_load_dwordx4 v[130:133], v4, s[38:39] nt
	s_add_u32 s38, s38, 0x10000
	s_addc_u32 s39, s39, 0
	global_load_dwordx4 v[134:137], v4, s[38:39] nt
	s_add_u32 s38, s38, 0x10000
	s_addc_u32 s39, s39, 0
	global_load_dwordx4 v[138:141], v4, s[38:39] nt
	s_add_u32 s38, s38, 0x10000
	s_addc_u32 s39, s39, 0
	global_load_dwordx4 v[142:145], v4, s[38:39] nt
	s_add_u32 s38, s38, 0x10000
	s_addc_u32 s39, s39, 0
	global_load_dwordx4 v[146:149], v4, s[38:39] nt
	s_add_u32 s38, s38, 0x10000
	s_addc_u32 s39, s39, 0
	global_load_dwordx4 v[150:153], v4, s[38:39] nt
	s_add_u32 s38, s38, 0x10000
	s_addc_u32 s39, s39, 0
	global_load_dwordx4 v[154:157], v4, s[38:39] nt
	s_addk_i32 s30, 0x180
	s_and_b32 s30, s30, 0x1fff
	s_waitcnt vmcnt(36)
	ds_write_b128 v110, v[158:161]
	ds_write_b128 v111, v[162:165] offset:1024
	ds_write_b128 v112, v[166:169] offset:2048
	ds_write_b128 v113, v[170:173] offset:3072
	ds_write_b128 v114, v[174:177] offset:4096
	ds_write_b128 v115, v[178:181] offset:5120
	ds_write_b128 v116, v[182:185] offset:6144
	ds_write_b128 v117, v[186:189] offset:7168
	ds_read2_b32 v[158:159], v118 offset1:32
	ds_read2_b32 v[160:161], v118 offset0:64 offset1:96
	ds_read2_b32 v[162:163], v118 offset0:128 offset1:160
	ds_read2_b32 v[164:165], v118 offset0:192 offset1:224
	ds_read2_b32 v[166:167], v119 offset1:32
	ds_read2_b32 v[168:169], v119 offset0:64 offset1:96
	ds_read2_b32 v[170:171], v119 offset0:128 offset1:160
	ds_read2_b32 v[172:173], v119 offset0:192 offset1:224
	ds_read2_b32 v[174:175], v120 offset1:32
	ds_read2_b32 v[176:177], v120 offset0:64 offset1:96
	ds_read2_b32 v[178:179], v120 offset0:128 offset1:160
	ds_read2_b32 v[180:181], v120 offset0:192 offset1:224
	ds_read2_b32 v[182:183], v121 offset1:32
	ds_read2_b32 v[184:185], v121 offset0:64 offset1:96
	ds_read2_b32 v[186:187], v121 offset0:128 offset1:160
	ds_read2_b32 v[188:189], v121 offset0:192 offset1:224
	s_lshr_b32 s34, s45, 6
	s_and_b32 s35, s45, 63
	s_lshl_b32 s36, s35, 19
	s_lshl_b32 s37, s34, 7
	s_add_i32 s36, s36, s37
	s_add_u32 s38, s28, s36
	s_addc_u32 s39, s29, 0
	s_waitcnt lgkmcnt(12)
	v_cvt_pk_bf16_f32 v94, v158, v159
	v_cvt_pk_bf16_f32 v95, v160, v161
	v_cvt_pk_bf16_f32 v96, v162, v163
	v_cvt_pk_bf16_f32 v97, v164, v165
	s_waitcnt lgkmcnt(8)
	v_cvt_pk_bf16_f32 v98, v166, v167
	v_cvt_pk_bf16_f32 v99, v168, v169
	v_cvt_pk_bf16_f32 v100, v170, v171
	v_cvt_pk_bf16_f32 v101, v172, v173
	s_waitcnt lgkmcnt(4)
	v_cvt_pk_bf16_f32 v102, v174, v175
	v_cvt_pk_bf16_f32 v103, v176, v177
	v_cvt_pk_bf16_f32 v104, v178, v179
	v_cvt_pk_bf16_f32 v105, v180, v181
	s_waitcnt lgkmcnt(0)
	v_cvt_pk_bf16_f32 v106, v182, v183
	v_cvt_pk_bf16_f32 v107, v184, v185
	v_cvt_pk_bf16_f32 v108, v186, v187
	v_cvt_pk_bf16_f32 v109, v188, v189
	global_store_dwordx4 v74, v[94:97], s[38:39]
	global_store_dwordx4 v75, v[98:101], s[38:39]
	global_store_dwordx4 v76, v[102:105], s[38:39]
	global_store_dwordx4 v77, v[106:109], s[38:39]
	s_lshr_b32 s34, s30, 6
	s_and_b32 s35, s30, 63
	s_mov_b32 s45, s30
	s_lshl_b32 s36, s34, 19
	s_lshl_b32 s37, s35, 7
	s_add_i32 s36, s36, s37
	s_add_u32 s38, s26, s36
	s_addc_u32 s39, s27, 0
	global_load_dwordx4 v[158:161], v4, s[38:39] nt
	s_add_u32 s38, s38, 0x10000
	s_addc_u32 s39, s39, 0
	global_load_dwordx4 v[162:165], v4, s[38:39] nt
	s_add_u32 s38, s38, 0x10000
	s_addc_u32 s39, s39, 0
	global_load_dwordx4 v[166:169], v4, s[38:39] nt
	s_add_u32 s38, s38, 0x10000
	s_addc_u32 s39, s39, 0
	global_load_dwordx4 v[170:173], v4, s[38:39] nt
	s_add_u32 s38, s38, 0x10000
	s_addc_u32 s39, s39, 0
	global_load_dwordx4 v[174:177], v4, s[38:39] nt
	s_add_u32 s38, s38, 0x10000
	s_addc_u32 s39, s39, 0
	global_load_dwordx4 v[178:181], v4, s[38:39] nt
	s_add_u32 s38, s38, 0x10000
	s_addc_u32 s39, s39, 0
	global_load_dwordx4 v[182:185], v4, s[38:39] nt
	s_add_u32 s38, s38, 0x10000
	s_addc_u32 s39, s39, 0
	global_load_dwordx4 v[186:189], v4, s[38:39] nt
	s_addk_i32 s30, 0x180
	s_and_b32 s30, s30, 0x1fff
	s_add_i32 s42, s42, -1
	s_cmp_lg_u32 s42, 0
	s_cbranch_scc1 .Ldw_w2_loop
	s_waitcnt vmcnt(36)
	ds_write_b128 v110, v[10:13]
	ds_write_b128 v111, v[14:17] offset:1024
	ds_write_b128 v112, v[18:21] offset:2048
	ds_write_b128 v113, v[22:25] offset:3072
	ds_write_b128 v114, v[26:29] offset:4096
	ds_write_b128 v115, v[30:33] offset:5120
	ds_write_b128 v116, v[34:37] offset:6144
	ds_write_b128 v117, v[38:41] offset:7168
	ds_read2_b32 v[10:11], v118 offset1:32
	ds_read2_b32 v[12:13], v118 offset0:64 offset1:96
	ds_read2_b32 v[14:15], v118 offset0:128 offset1:160
	ds_read2_b32 v[16:17], v118 offset0:192 offset1:224
	ds_read2_b32 v[18:19], v119 offset1:32
	ds_read2_b32 v[20:21], v119 offset0:64 offset1:96
	ds_read2_b32 v[22:23], v119 offset0:128 offset1:160
	ds_read2_b32 v[24:25], v119 offset0:192 offset1:224
	ds_read2_b32 v[26:27], v120 offset1:32
	ds_read2_b32 v[28:29], v120 offset0:64 offset1:96
	ds_read2_b32 v[30:31], v120 offset0:128 offset1:160
	ds_read2_b32 v[32:33], v120 offset0:192 offset1:224
	ds_read2_b32 v[34:35], v121 offset1:32
	ds_read2_b32 v[36:37], v121 offset0:64 offset1:96
	ds_read2_b32 v[38:39], v121 offset0:128 offset1:160
	ds_read2_b32 v[40:41], v121 offset0:192 offset1:224
	s_lshr_b32 s34, s40, 6
	s_and_b32 s35, s40, 63
	s_lshl_b32 s36, s35, 19
	s_lshl_b32 s37, s34, 7
	s_add_i32 s36, s36, s37
	s_add_u32 s38, s28, s36
	s_addc_u32 s39, s29, 0
	s_waitcnt lgkmcnt(12)
	v_cvt_pk_bf16_f32 v78, v10, v11
	v_cvt_pk_bf16_f32 v79, v12, v13
	v_cvt_pk_bf16_f32 v80, v14, v15
	v_cvt_pk_bf16_f32 v81, v16, v17
	s_waitcnt lgkmcnt(8)
	v_cvt_pk_bf16_f32 v82, v18, v19
	v_cvt_pk_bf16_f32 v83, v20, v21
	v_cvt_pk_bf16_f32 v84, v22, v23
	v_cvt_pk_bf16_f32 v85, v24, v25
	s_waitcnt lgkmcnt(4)
	v_cvt_pk_bf16_f32 v86, v26, v27
	v_cvt_pk_bf16_f32 v87, v28, v29
	v_cvt_pk_bf16_f32 v88, v30, v31
	v_cvt_pk_bf16_f32 v89, v32, v33
	s_waitcnt lgkmcnt(0)
	v_cvt_pk_bf16_f32 v90, v34, v35
	v_cvt_pk_bf16_f32 v91, v36, v37
	v_cvt_pk_bf16_f32 v92, v38, v39
	v_cvt_pk_bf16_f32 v93, v40, v41
	global_store_dwordx4 v74, v[78:81], s[38:39]
	global_store_dwordx4 v75, v[82:85], s[38:39]
	global_store_dwordx4 v76, v[86:89], s[38:39]
	global_store_dwordx4 v77, v[90:93], s[38:39]
	s_waitcnt vmcnt(28)
	ds_write_b128 v110, v[42:45]
	ds_write_b128 v111, v[46:49] offset:1024
	ds_write_b128 v112, v[50:53] offset:2048
	ds_write_b128 v113, v[54:57] offset:3072
	ds_write_b128 v114, v[58:61] offset:4096
	ds_write_b128 v115, v[62:65] offset:5120
	ds_write_b128 v116, v[66:69] offset:6144
	ds_write_b128 v117, v[70:73] offset:7168
	ds_read2_b32 v[42:43], v118 offset1:32
	ds_read2_b32 v[44:45], v118 offset0:64 offset1:96
	ds_read2_b32 v[46:47], v118 offset0:128 offset1:160
	ds_read2_b32 v[48:49], v118 offset0:192 offset1:224
	ds_read2_b32 v[50:51], v119 offset1:32
	ds_read2_b32 v[52:53], v119 offset0:64 offset1:96
	ds_read2_b32 v[54:55], v119 offset0:128 offset1:160
	ds_read2_b32 v[56:57], v119 offset0:192 offset1:224
	ds_read2_b32 v[58:59], v120 offset1:32
	ds_read2_b32 v[60:61], v120 offset0:64 offset1:96
	ds_read2_b32 v[62:63], v120 offset0:128 offset1:160
	ds_read2_b32 v[64:65], v120 offset0:192 offset1:224
	ds_read2_b32 v[66:67], v121 offset1:32
	ds_read2_b32 v[68:69], v121 offset0:64 offset1:96
	ds_read2_b32 v[70:71], v121 offset0:128 offset1:160
	ds_read2_b32 v[72:73], v121 offset0:192 offset1:224
	s_lshr_b32 s34, s41, 6
	s_and_b32 s35, s41, 63
	s_lshl_b32 s36, s35, 19
	s_lshl_b32 s37, s34, 7
	s_add_i32 s36, s36, s37
	s_add_u32 s38, s28, s36
	s_addc_u32 s39, s29, 0
	s_waitcnt lgkmcnt(12)
	v_cvt_pk_bf16_f32 v94, v42, v43
	v_cvt_pk_bf16_f32 v95, v44, v45
	v_cvt_pk_bf16_f32 v96, v46, v47
	v_cvt_pk_bf16_f32 v97, v48, v49
	s_waitcnt lgkmcnt(8)
	v_cvt_pk_bf16_f32 v98, v50, v51
	v_cvt_pk_bf16_f32 v99, v52, v53
	v_cvt_pk_bf16_f32 v100, v54, v55
	v_cvt_pk_bf16_f32 v101, v56, v57
	s_waitcnt lgkmcnt(4)
	v_cvt_pk_bf16_f32 v102, v58, v59
	v_cvt_pk_bf16_f32 v103, v60, v61
	v_cvt_pk_bf16_f32 v104, v62, v63
	v_cvt_pk_bf16_f32 v105, v64, v65
	s_waitcnt lgkmcnt(0)
	v_cvt_pk_bf16_f32 v106, v66, v67
	v_cvt_pk_bf16_f32 v107, v68, v69
	v_cvt_pk_bf16_f32 v108, v70, v71
	v_cvt_pk_bf16_f32 v109, v72, v73
	global_store_dwordx4 v74, v[94:97], s[38:39]
	global_store_dwordx4 v75, v[98:101], s[38:39]
	global_store_dwordx4 v76, v[102:105], s[38:39]
	global_store_dwordx4 v77, v[106:109], s[38:39]
	s_waitcnt vmcnt(20)
	ds_write_b128 v110, v[126:129]
	ds_write_b128 v111, v[130:133] offset:1024
	ds_write_b128 v112, v[134:137] offset:2048
	ds_write_b128 v113, v[138:141] offset:3072
	ds_write_b128 v114, v[142:145] offset:4096
	ds_write_b128 v115, v[146:149] offset:5120
	ds_write_b128 v116, v[150:153] offset:6144
	ds_write_b128 v117, v[154:157] offset:7168
	ds_read2_b32 v[126:127], v118 offset1:32
	ds_read2_b32 v[128:129], v118 offset0:64 offset1:96
	ds_read2_b32 v[130:131], v118 offset0:128 offset1:160
	ds_read2_b32 v[132:133], v118 offset0:192 offset1:224
	ds_read2_b32 v[134:135], v119 offset1:32
	ds_read2_b32 v[136:137], v119 offset0:64 offset1:96
	ds_read2_b32 v[138:139], v119 offset0:128 offset1:160
	ds_read2_b32 v[140:141], v119 offset0:192 offset1:224
	ds_read2_b32 v[142:143], v120 offset1:32
	ds_read2_b32 v[144:145], v120 offset0:64 offset1:96
	ds_read2_b32 v[146:147], v120 offset0:128 offset1:160
	ds_read2_b32 v[148:149], v120 offset0:192 offset1:224
	ds_read2_b32 v[150:151], v121 offset1:32
	ds_read2_b32 v[152:153], v121 offset0:64 offset1:96
	ds_read2_b32 v[154:155], v121 offset0:128 offset1:160
	ds_read2_b32 v[156:157], v121 offset0:192 offset1:224
	s_lshr_b32 s34, s44, 6
	s_and_b32 s35, s44, 63
	s_lshl_b32 s36, s35, 19
	s_lshl_b32 s37, s34, 7
	s_add_i32 s36, s36, s37
	s_add_u32 s38, s28, s36
	s_addc_u32 s39, s29, 0
	s_waitcnt lgkmcnt(12)
	v_cvt_pk_bf16_f32 v78, v126, v127
	v_cvt_pk_bf16_f32 v79, v128, v129
	v_cvt_pk_bf16_f32 v80, v130, v131
	v_cvt_pk_bf16_f32 v81, v132, v133
	s_waitcnt lgkmcnt(8)
	v_cvt_pk_bf16_f32 v82, v134, v135
	v_cvt_pk_bf16_f32 v83, v136, v137
	v_cvt_pk_bf16_f32 v84, v138, v139
	v_cvt_pk_bf16_f32 v85, v140, v141
	s_waitcnt lgkmcnt(4)
	v_cvt_pk_bf16_f32 v86, v142, v143
	v_cvt_pk_bf16_f32 v87, v144, v145
	v_cvt_pk_bf16_f32 v88, v146, v147
	v_cvt_pk_bf16_f32 v89, v148, v149
	s_waitcnt lgkmcnt(0)
	v_cvt_pk_bf16_f32 v90, v150, v151
	v_cvt_pk_bf16_f32 v91, v152, v153
	v_cvt_pk_bf16_f32 v92, v154, v155
	v_cvt_pk_bf16_f32 v93, v156, v157
	global_store_dwordx4 v74, v[78:81], s[38:39]
	global_store_dwordx4 v75, v[82:85], s[38:39]
	global_store_dwordx4 v76, v[86:89], s[38:39]
	global_store_dwordx4 v77, v[90:93], s[38:39]
	s_waitcnt vmcnt(12)
	ds_write_b128 v110, v[158:161]
	ds_write_b128 v111, v[162:165] offset:1024
	ds_write_b128 v112, v[166:169] offset:2048
	ds_write_b128 v113, v[170:173] offset:3072
	ds_write_b128 v114, v[174:177] offset:4096
	ds_write_b128 v115, v[178:181] offset:5120
	ds_write_b128 v116, v[182:185] offset:6144
	ds_write_b128 v117, v[186:189] offset:7168
	ds_read2_b32 v[158:159], v118 offset1:32
	ds_read2_b32 v[160:161], v118 offset0:64 offset1:96
	ds_read2_b32 v[162:163], v118 offset0:128 offset1:160
	ds_read2_b32 v[164:165], v118 offset0:192 offset1:224
	ds_read2_b32 v[166:167], v119 offset1:32
	ds_read2_b32 v[168:169], v119 offset0:64 offset1:96
	ds_read2_b32 v[170:171], v119 offset0:128 offset1:160
	ds_read2_b32 v[172:173], v119 offset0:192 offset1:224
	ds_read2_b32 v[174:175], v120 offset1:32
	ds_read2_b32 v[176:177], v120 offset0:64 offset1:96
	ds_read2_b32 v[178:179], v120 offset0:128 offset1:160
	ds_read2_b32 v[180:181], v120 offset0:192 offset1:224
	ds_read2_b32 v[182:183], v121 offset1:32
	ds_read2_b32 v[184:185], v121 offset0:64 offset1:96
	ds_read2_b32 v[186:187], v121 offset0:128 offset1:160
	ds_read2_b32 v[188:189], v121 offset0:192 offset1:224
	s_lshr_b32 s34, s45, 6
	s_and_b32 s35, s45, 63
	s_lshl_b32 s36, s35, 19
	s_lshl_b32 s37, s34, 7
	s_add_i32 s36, s36, s37
	s_add_u32 s38, s28, s36
	s_addc_u32 s39, s29, 0
	s_waitcnt lgkmcnt(12)
	v_cvt_pk_bf16_f32 v94, v158, v159
	v_cvt_pk_bf16_f32 v95, v160, v161
	v_cvt_pk_bf16_f32 v96, v162, v163
	v_cvt_pk_bf16_f32 v97, v164, v165
	s_waitcnt lgkmcnt(8)
	v_cvt_pk_bf16_f32 v98, v166, v167
	v_cvt_pk_bf16_f32 v99, v168, v169
	v_cvt_pk_bf16_f32 v100, v170, v171
	v_cvt_pk_bf16_f32 v101, v172, v173
	s_waitcnt lgkmcnt(4)
	v_cvt_pk_bf16_f32 v102, v174, v175
	v_cvt_pk_bf16_f32 v103, v176, v177
	v_cvt_pk_bf16_f32 v104, v178, v179
	v_cvt_pk_bf16_f32 v105, v180, v181
	s_waitcnt lgkmcnt(0)
	v_cvt_pk_bf16_f32 v106, v182, v183
	v_cvt_pk_bf16_f32 v107, v184, v185
	v_cvt_pk_bf16_f32 v108, v186, v187
	v_cvt_pk_bf16_f32 v109, v188, v189
	global_store_dwordx4 v74, v[94:97], s[38:39]
	global_store_dwordx4 v75, v[98:101], s[38:39]
	global_store_dwordx4 v76, v[102:105], s[38:39]
	global_store_dwordx4 v77, v[106:109], s[38:39]
	s_waitcnt vmcnt(0) lgkmcnt(0)
	s_load_dwordx2 s[26:27], s[86:87], 0xb0
	s_load_dwordx2 s[28:29], s[86:87], 0x118
	s_mov_b32 s30, s43
	v_lshlrev_b32_e32 v74, 12, v2
	v_lshl_add_u32 v74, v3, 4, v74
	v_add_u32_e32 v75, 0x8000, v74
	v_add_u32_e32 v76, 0x10000, v74
	v_add_u32_e32 v77, 0x18000, v74
	s_waitcnt lgkmcnt(0)
	s_add_u32 s28, s28, 0x6700000
	s_addc_u32 s29, s29, 0
	s_lshr_b32 s34, s30, 6
	s_and_b32 s35, s30, 63
	s_mov_b32 s40, s30
	s_lshl_b32 s36, s34, 19
	s_lshl_b32 s37, s35, 7
	s_add_i32 s36, s36, s37
	s_add_u32 s38, s26, s36
	s_addc_u32 s39, s27, 0
	global_load_dwordx4 v[10:13], v4, s[38:39] nt
	s_add_u32 s38, s38, 0x10000
	s_addc_u32 s39, s39, 0
	global_load_dwordx4 v[14:17], v4, s[38:39] nt
	s_add_u32 s38, s38, 0x10000
	s_addc_u32 s39, s39, 0
	global_load_dwordx4 v[18:21], v4, s[38:39] nt
	s_add_u32 s38, s38, 0x10000
	s_addc_u32 s39, s39, 0
	global_load_dwordx4 v[22:25], v4, s[38:39] nt
	s_add_u32 s38, s38, 0x10000
	s_addc_u32 s39, s39, 0
	global_load_dwordx4 v[26:29], v4, s[38:39] nt
	s_add_u32 s38, s38, 0x10000
	s_addc_u32 s39, s39, 0
	global_load_dwordx4 v[30:33], v4, s[38:39] nt
	s_add_u32 s38, s38, 0x10000
	s_addc_u32 s39, s39, 0
	global_load_dwordx4 v[34:37], v4, s[38:39] nt
	s_add_u32 s38, s38, 0x10000
	s_addc_u32 s39, s39, 0
	global_load_dwordx4 v[38:41], v4, s[38:39] nt
	s_addk_i32 s30, 0x180
	s_and_b32 s30, s30, 0x7ff
	s_lshr_b32 s34, s30, 6
	s_and_b32 s35, s30, 63
	s_mov_b32 s41, s30
	s_lshl_b32 s36, s34, 19
	s_lshl_b32 s37, s35, 7
	s_add_i32 s36, s36, s37
	s_add_u32 s38, s26, s36
	s_addc_u32 s39, s27, 0
	global_load_dwordx4 v[42:45], v4, s[38:39] nt
	s_add_u32 s38, s38, 0x10000
	s_addc_u32 s39, s39, 0
	global_load_dwordx4 v[46:49], v4, s[38:39] nt
	s_add_u32 s38, s38, 0x10000
	s_addc_u32 s39, s39, 0
	global_load_dwordx4 v[50:53], v4, s[38:39] nt
	s_add_u32 s38, s38, 0x10000
	s_addc_u32 s39, s39, 0
	global_load_dwordx4 v[54:57], v4, s[38:39] nt
	s_add_u32 s38, s38, 0x10000
	s_addc_u32 s39, s39, 0
	global_load_dwordx4 v[58:61], v4, s[38:39] nt
	s_add_u32 s38, s38, 0x10000
	s_addc_u32 s39, s39, 0
	global_load_dwordx4 v[62:65], v4, s[38:39] nt
	s_add_u32 s38, s38, 0x10000
	s_addc_u32 s39, s39, 0
	global_load_dwordx4 v[66:69], v4, s[38:39] nt
	s_add_u32 s38, s38, 0x10000
	s_addc_u32 s39, s39, 0
	global_load_dwordx4 v[70:73], v4, s[38:39] nt
	s_addk_i32 s30, 0x180
	s_and_b32 s30, s30, 0x7ff
	s_lshr_b32 s34, s30, 6
	s_and_b32 s35, s30, 63
	s_mov_b32 s44, s30
	s_lshl_b32 s36, s34, 19
	s_lshl_b32 s37, s35, 7
	s_add_i32 s36, s36, s37
	s_add_u32 s38, s26, s36
	s_addc_u32 s39, s27, 0
	global_load_dwordx4 v[126:129], v4, s[38:39] nt
	s_add_u32 s38, s38, 0x10000
	s_addc_u32 s39, s39, 0
	global_load_dwordx4 v[130:133], v4, s[38:39] nt
	s_add_u32 s38, s38, 0x10000
	s_addc_u32 s39, s39, 0
	global_load_dwordx4 v[134:137], v4, s[38:39] nt
	s_add_u32 s38, s38, 0x10000
	s_addc_u32 s39, s39, 0
	global_load_dwordx4 v[138:141], v4, s[38:39] nt
	s_add_u32 s38, s38, 0x10000
	s_addc_u32 s39, s39, 0
	global_load_dwordx4 v[142:145], v4, s[38:39] nt
	s_add_u32 s38, s38, 0x10000
	s_addc_u32 s39, s39, 0
	global_load_dwordx4 v[146:149], v4, s[38:39] nt
	s_add_u32 s38, s38, 0x10000
	s_addc_u32 s39, s39, 0
	global_load_dwordx4 v[150:153], v4, s[38:39] nt
	s_add_u32 s38, s38, 0x10000
	s_addc_u32 s39, s39, 0
	global_load_dwordx4 v[154:157], v4, s[38:39] nt
	s_addk_i32 s30, 0x180
	s_and_b32 s30, s30, 0x7ff
	s_lshr_b32 s34, s30, 6
	s_and_b32 s35, s30, 63
	s_mov_b32 s45, s30
	s_lshl_b32 s36, s34, 19
	s_lshl_b32 s37, s35, 7
	s_add_i32 s36, s36, s37
	s_add_u32 s38, s26, s36
	s_addc_u32 s39, s27, 0
	global_load_dwordx4 v[158:161], v4, s[38:39] nt
	s_add_u32 s38, s38, 0x10000
	s_addc_u32 s39, s39, 0
	global_load_dwordx4 v[162:165], v4, s[38:39] nt
	s_add_u32 s38, s38, 0x10000
	s_addc_u32 s39, s39, 0
	global_load_dwordx4 v[166:169], v4, s[38:39] nt
	s_add_u32 s38, s38, 0x10000
	s_addc_u32 s39, s39, 0
	global_load_dwordx4 v[170:173], v4, s[38:39] nt
	s_add_u32 s38, s38, 0x10000
	s_addc_u32 s39, s39, 0
	global_load_dwordx4 v[174:177], v4, s[38:39] nt
	s_add_u32 s38, s38, 0x10000
	s_addc_u32 s39, s39, 0
	global_load_dwordx4 v[178:181], v4, s[38:39] nt
	s_add_u32 s38, s38, 0x10000
	s_addc_u32 s39, s39, 0
	global_load_dwordx4 v[182:185], v4, s[38:39] nt
	s_add_u32 s38, s38, 0x10000
	s_addc_u32 s39, s39, 0
	global_load_dwordx4 v[186:189], v4, s[38:39] nt
	s_addk_i32 s30, 0x180
	s_and_b32 s30, s30, 0x7ff
	s_waitcnt vmcnt(24)
	ds_write_b128 v110, v[10:13]
	ds_write_b128 v111, v[14:17] offset:1024
	ds_write_b128 v112, v[18:21] offset:2048
	ds_write_b128 v113, v[22:25] offset:3072
	ds_write_b128 v114, v[26:29] offset:4096
	ds_write_b128 v115, v[30:33] offset:5120
	ds_write_b128 v116, v[34:37] offset:6144
	ds_write_b128 v117, v[38:41] offset:7168
	ds_read2_b32 v[10:11], v118 offset1:32
	ds_read2_b32 v[12:13], v118 offset0:64 offset1:96
	ds_read2_b32 v[14:15], v118 offset0:128 offset1:160
	ds_read2_b32 v[16:17], v118 offset0:192 offset1:224
	ds_read2_b32 v[18:19], v119 offset1:32
	ds_read2_b32 v[20:21], v119 offset0:64 offset1:96
	ds_read2_b32 v[22:23], v119 offset0:128 offset1:160
	ds_read2_b32 v[24:25], v119 offset0:192 offset1:224
	ds_read2_b32 v[26:27], v120 offset1:32
	ds_read2_b32 v[28:29], v120 offset0:64 offset1:96
	ds_read2_b32 v[30:31], v120 offset0:128 offset1:160
	ds_read2_b32 v[32:33], v120 offset0:192 offset1:224
	ds_read2_b32 v[34:35], v121 offset1:32
	ds_read2_b32 v[36:37], v121 offset0:64 offset1:96
	ds_read2_b32 v[38:39], v121 offset0:128 offset1:160
	ds_read2_b32 v[40:41], v121 offset0:192 offset1:224
	s_lshr_b32 s34, s40, 6
	s_and_b32 s35, s40, 63
	s_lshl_b32 s36, s35, 17
	s_lshl_b32 s37, s34, 7
	s_add_i32 s36, s36, s37
	s_add_u32 s38, s28, s36
	s_addc_u32 s39, s29, 0
	s_waitcnt lgkmcnt(12)
	v_cvt_pk_bf16_f32 v78, v10, v11
	v_cvt_pk_bf16_f32 v79, v12, v13
	v_cvt_pk_bf16_f32 v80, v14, v15
	v_cvt_pk_bf16_f32 v81, v16, v17
	s_waitcnt lgkmcnt(8)
	v_cvt_pk_bf16_f32 v82, v18, v19
	v_cvt_pk_bf16_f32 v83, v20, v21
	v_cvt_pk_bf16_f32 v84, v22, v23
	v_cvt_pk_bf16_f32 v85, v24, v25
	s_waitcnt lgkmcnt(4)
	v_cvt_pk_bf16_f32 v86, v26, v27
	v_cvt_pk_bf16_f32 v87, v28, v29
	v_cvt_pk_bf16_f32 v88, v30, v31
	v_cvt_pk_bf16_f32 v89, v32, v33
	s_waitcnt lgkmcnt(0)
	v_cvt_pk_bf16_f32 v90, v34, v35
	v_cvt_pk_bf16_f32 v91, v36, v37
	v_cvt_pk_bf16_f32 v92, v38, v39
	v_cvt_pk_bf16_f32 v93, v40, v41
	global_store_dwordx4 v74, v[78:81], s[38:39]
	global_store_dwordx4 v75, v[82:85], s[38:39]
	global_store_dwordx4 v76, v[86:89], s[38:39]
	global_store_dwordx4 v77, v[90:93], s[38:39]
	s_lshr_b32 s34, s30, 6
	s_and_b32 s35, s30, 63
	s_mov_b32 s40, s30
	s_lshl_b32 s36, s34, 19
	s_lshl_b32 s37, s35, 7
	s_add_i32 s36, s36, s37
	s_add_u32 s38, s26, s36
	s_addc_u32 s39, s27, 0
	global_load_dwordx4 v[10:13], v4, s[38:39] nt
	s_add_u32 s38, s38, 0x10000
	s_addc_u32 s39, s39, 0
	global_load_dwordx4 v[14:17], v4, s[38:39] nt
	s_add_u32 s38, s38, 0x10000
	s_addc_u32 s39, s39, 0
	global_load_dwordx4 v[18:21], v4, s[38:39] nt
	s_add_u32 s38, s38, 0x10000
	s_addc_u32 s39, s39, 0
	global_load_dwordx4 v[22:25], v4, s[38:39] nt
	s_add_u32 s38, s38, 0x10000
	s_addc_u32 s39, s39, 0
	global_load_dwordx4 v[26:29], v4, s[38:39] nt
	s_add_u32 s38, s38, 0x10000
	s_addc_u32 s39, s39, 0
	global_load_dwordx4 v[30:33], v4, s[38:39] nt
	s_add_u32 s38, s38, 0x10000
	s_addc_u32 s39, s39, 0
	global_load_dwordx4 v[34:37], v4, s[38:39] nt
	s_add_u32 s38, s38, 0x10000
	s_addc_u32 s39, s39, 0
	global_load_dwordx4 v[38:41], v4, s[38:39] nt
	s_addk_i32 s30, 0x180
	s_and_b32 s30, s30, 0x7ff
	s_waitcnt vmcnt(28)
	ds_write_b128 v110, v[42:45]
	ds_write_b128 v111, v[46:49] offset:1024
	ds_write_b128 v112, v[50:53] offset:2048
	ds_write_b128 v113, v[54:57] offset:3072
	ds_write_b128 v114, v[58:61] offset:4096
	ds_write_b128 v115, v[62:65] offset:5120
	ds_write_b128 v116, v[66:69] offset:6144
	ds_write_b128 v117, v[70:73] offset:7168
	ds_read2_b32 v[42:43], v118 offset1:32
	ds_read2_b32 v[44:45], v118 offset0:64 offset1:96
	ds_read2_b32 v[46:47], v118 offset0:128 offset1:160
	ds_read2_b32 v[48:49], v118 offset0:192 offset1:224
	ds_read2_b32 v[50:51], v119 offset1:32
	ds_read2_b32 v[52:53], v119 offset0:64 offset1:96
	ds_read2_b32 v[54:55], v119 offset0:128 offset1:160
	ds_read2_b32 v[56:57], v119 offset0:192 offset1:224
	ds_read2_b32 v[58:59], v120 offset1:32
	ds_read2_b32 v[60:61], v120 offset0:64 offset1:96
	ds_read2_b32 v[62:63], v120 offset0:128 offset1:160
	ds_read2_b32 v[64:65], v120 offset0:192 offset1:224
	ds_read2_b32 v[66:67], v121 offset1:32
	ds_read2_b32 v[68:69], v121 offset0:64 offset1:96
	ds_read2_b32 v[70:71], v121 offset0:128 offset1:160
	ds_read2_b32 v[72:73], v121 offset0:192 offset1:224
	s_lshr_b32 s34, s41, 6
	s_and_b32 s35, s41, 63
	s_lshl_b32 s36, s35, 17
	s_lshl_b32 s37, s34, 7
	s_add_i32 s36, s36, s37
	s_add_u32 s38, s28, s36
	s_addc_u32 s39, s29, 0
	s_waitcnt lgkmcnt(12)
	v_cvt_pk_bf16_f32 v94, v42, v43
	v_cvt_pk_bf16_f32 v95, v44, v45
	v_cvt_pk_bf16_f32 v96, v46, v47
	v_cvt_pk_bf16_f32 v97, v48, v49
	s_waitcnt lgkmcnt(8)
	v_cvt_pk_bf16_f32 v98, v50, v51
	v_cvt_pk_bf16_f32 v99, v52, v53
	v_cvt_pk_bf16_f32 v100, v54, v55
	v_cvt_pk_bf16_f32 v101, v56, v57
	s_waitcnt lgkmcnt(4)
	v_cvt_pk_bf16_f32 v102, v58, v59
	v_cvt_pk_bf16_f32 v103, v60, v61
	v_cvt_pk_bf16_f32 v104, v62, v63
	v_cvt_pk_bf16_f32 v105, v64, v65
	s_waitcnt lgkmcnt(0)
	v_cvt_pk_bf16_f32 v106, v66, v67
	v_cvt_pk_bf16_f32 v107, v68, v69
	v_cvt_pk_bf16_f32 v108, v70, v71
	v_cvt_pk_bf16_f32 v109, v72, v73
	global_store_dwordx4 v74, v[94:97], s[38:39]
	global_store_dwordx4 v75, v[98:101], s[38:39]
	global_store_dwordx4 v76, v[102:105], s[38:39]
	global_store_dwordx4 v77, v[106:109], s[38:39]
	s_lshr_b32 s34, s30, 6
	s_and_b32 s35, s30, 63
	s_mov_b32 s41, s30
	s_lshl_b32 s36, s34, 19
	s_lshl_b32 s37, s35, 7
	s_add_i32 s36, s36, s37
	s_add_u32 s38, s26, s36
	s_addc_u32 s39, s27, 0
	global_load_dwordx4 v[42:45], v4, s[38:39] nt
	s_add_u32 s38, s38, 0x10000
	s_addc_u32 s39, s39, 0
	global_load_dwordx4 v[46:49], v4, s[38:39] nt
	s_add_u32 s38, s38, 0x10000
	s_addc_u32 s39, s39, 0
	global_load_dwordx4 v[50:53], v4, s[38:39] nt
	s_add_u32 s38, s38, 0x10000
	s_addc_u32 s39, s39, 0
	global_load_dwordx4 v[54:57], v4, s[38:39] nt
	s_add_u32 s38, s38, 0x10000
	s_addc_u32 s39, s39, 0
	global_load_dwordx4 v[58:61], v4, s[38:39] nt
	s_add_u32 s38, s38, 0x10000
	s_addc_u32 s39, s39, 0
	global_load_dwordx4 v[62:65], v4, s[38:39] nt
	s_add_u32 s38, s38, 0x10000
	s_addc_u32 s39, s39, 0
	global_load_dwordx4 v[66:69], v4, s[38:39] nt
	s_add_u32 s38, s38, 0x10000
	s_addc_u32 s39, s39, 0
	global_load_dwordx4 v[70:73], v4, s[38:39] nt
	s_addk_i32 s30, 0x180
	s_and_b32 s30, s30, 0x7ff
	s_waitcnt vmcnt(32)
	ds_write_b128 v110, v[126:129]
	ds_write_b128 v111, v[130:133] offset:1024
	ds_write_b128 v112, v[134:137] offset:2048
	ds_write_b128 v113, v[138:141] offset:3072
	ds_write_b128 v114, v[142:145] offset:4096
	ds_write_b128 v115, v[146:149] offset:5120
	ds_write_b128 v116, v[150:153] offset:6144
	ds_write_b128 v117, v[154:157] offset:7168
	ds_read2_b32 v[126:127], v118 offset1:32
	ds_read2_b32 v[128:129], v118 offset0:64 offset1:96
	ds_read2_b32 v[130:131], v118 offset0:128 offset1:160
	ds_read2_b32 v[132:133], v118 offset0:192 offset1:224
	ds_read2_b32 v[134:135], v119 offset1:32
	ds_read2_b32 v[136:137], v119 offset0:64 offset1:96
	ds_read2_b32 v[138:139], v119 offset0:128 offset1:160
	ds_read2_b32 v[140:141], v119 offset0:192 offset1:224
	ds_read2_b32 v[142:143], v120 offset1:32
	ds_read2_b32 v[144:145], v120 offset0:64 offset1:96
	ds_read2_b32 v[146:147], v120 offset0:128 offset1:160
	ds_read2_b32 v[148:149], v120 offset0:192 offset1:224
	ds_read2_b32 v[150:151], v121 offset1:32
	ds_read2_b32 v[152:153], v121 offset0:64 offset1:96
	ds_read2_b32 v[154:155], v121 offset0:128 offset1:160
	ds_read2_b32 v[156:157], v121 offset0:192 offset1:224
	s_lshr_b32 s34, s44, 6
	s_and_b32 s35, s44, 63
	s_lshl_b32 s36, s35, 17
	s_lshl_b32 s37, s34, 7
	s_add_i32 s36, s36, s37
	s_add_u32 s38, s28, s36
	s_addc_u32 s39, s29, 0
	s_waitcnt lgkmcnt(12)
	v_cvt_pk_bf16_f32 v78, v126, v127
	v_cvt_pk_bf16_f32 v79, v128, v129
	v_cvt_pk_bf16_f32 v80, v130, v131
	v_cvt_pk_bf16_f32 v81, v132, v133
	s_waitcnt lgkmcnt(8)
	v_cvt_pk_bf16_f32 v82, v134, v135
	v_cvt_pk_bf16_f32 v83, v136, v137
	v_cvt_pk_bf16_f32 v84, v138, v139
	v_cvt_pk_bf16_f32 v85, v140, v141
	s_waitcnt lgkmcnt(4)
	v_cvt_pk_bf16_f32 v86, v142, v143
	v_cvt_pk_bf16_f32 v87, v144, v145
	v_cvt_pk_bf16_f32 v88, v146, v147
	v_cvt_pk_bf16_f32 v89, v148, v149
	s_waitcnt lgkmcnt(0)
	v_cvt_pk_bf16_f32 v90, v150, v151
	v_cvt_pk_bf16_f32 v91, v152, v153
	v_cvt_pk_bf16_f32 v92, v154, v155
	v_cvt_pk_bf16_f32 v93, v156, v157
	global_store_dwordx4 v74, v[78:81], s[38:39]
	global_store_dwordx4 v75, v[82:85], s[38:39]
	global_store_dwordx4 v76, v[86:89], s[38:39]
	global_store_dwordx4 v77, v[90:93], s[38:39]
	s_lshr_b32 s34, s30, 6
	s_and_b32 s35, s30, 63
	s_mov_b32 s44, s30
	s_lshl_b32 s36, s34, 19
	s_lshl_b32 s37, s35, 7
	s_add_i32 s36, s36, s37
	s_add_u32 s38, s26, s36
	s_addc_u32 s39, s27, 0
	global_load_dwordx4 v[126:129], v4, s[38:39] nt
	s_add_u32 s38, s38, 0x10000
	s_addc_u32 s39, s39, 0
	global_load_dwordx4 v[130:133], v4, s[38:39] nt
	s_add_u32 s38, s38, 0x10000
	s_addc_u32 s39, s39, 0
	global_load_dwordx4 v[134:137], v4, s[38:39] nt
	s_add_u32 s38, s38, 0x10000
	s_addc_u32 s39, s39, 0
	global_load_dwordx4 v[138:141], v4, s[38:39] nt
	s_add_u32 s38, s38, 0x10000
	s_addc_u32 s39, s39, 0
	global_load_dwordx4 v[142:145], v4, s[38:39] nt
	s_add_u32 s38, s38, 0x10000
	s_addc_u32 s39, s39, 0
	global_load_dwordx4 v[146:149], v4, s[38:39] nt
	s_add_u32 s38, s38, 0x10000
	s_addc_u32 s39, s39, 0
	global_load_dwordx4 v[150:153], v4, s[38:39] nt
	s_add_u32 s38, s38, 0x10000
	s_addc_u32 s39, s39, 0
	global_load_dwordx4 v[154:157], v4, s[38:39] nt
	s_addk_i32 s30, 0x180
	s_and_b32 s30, s30, 0x7ff
	s_waitcnt vmcnt(36)
	ds_write_b128 v110, v[158:161]
	ds_write_b128 v111, v[162:165] offset:1024
	ds_write_b128 v112, v[166:169] offset:2048
	ds_write_b128 v113, v[170:173] offset:3072
	ds_write_b128 v114, v[174:177] offset:4096
	ds_write_b128 v115, v[178:181] offset:5120
	ds_write_b128 v116, v[182:185] offset:6144
	ds_write_b128 v117, v[186:189] offset:7168
	ds_read2_b32 v[158:159], v118 offset1:32
	ds_read2_b32 v[160:161], v118 offset0:64 offset1:96
	ds_read2_b32 v[162:163], v118 offset0:128 offset1:160
	ds_read2_b32 v[164:165], v118 offset0:192 offset1:224
	ds_read2_b32 v[166:167], v119 offset1:32
	ds_read2_b32 v[168:169], v119 offset0:64 offset1:96
	ds_read2_b32 v[170:171], v119 offset0:128 offset1:160
	ds_read2_b32 v[172:173], v119 offset0:192 offset1:224
	ds_read2_b32 v[174:175], v120 offset1:32
	ds_read2_b32 v[176:177], v120 offset0:64 offset1:96
	ds_read2_b32 v[178:179], v120 offset0:128 offset1:160
	ds_read2_b32 v[180:181], v120 offset0:192 offset1:224
	ds_read2_b32 v[182:183], v121 offset1:32
	ds_read2_b32 v[184:185], v121 offset0:64 offset1:96
	ds_read2_b32 v[186:187], v121 offset0:128 offset1:160
	ds_read2_b32 v[188:189], v121 offset0:192 offset1:224
	s_lshr_b32 s34, s45, 6
	s_and_b32 s35, s45, 63
	s_lshl_b32 s36, s35, 17
	s_lshl_b32 s37, s34, 7
	s_add_i32 s36, s36, s37
	s_add_u32 s38, s28, s36
	s_addc_u32 s39, s29, 0
	s_waitcnt lgkmcnt(12)
	v_cvt_pk_bf16_f32 v94, v158, v159
	v_cvt_pk_bf16_f32 v95, v160, v161
	v_cvt_pk_bf16_f32 v96, v162, v163
	v_cvt_pk_bf16_f32 v97, v164, v165
	s_waitcnt lgkmcnt(8)
	v_cvt_pk_bf16_f32 v98, v166, v167
	v_cvt_pk_bf16_f32 v99, v168, v169
	v_cvt_pk_bf16_f32 v100, v170, v171
	v_cvt_pk_bf16_f32 v101, v172, v173
	s_waitcnt lgkmcnt(4)
	v_cvt_pk_bf16_f32 v102, v174, v175
	v_cvt_pk_bf16_f32 v103, v176, v177
	v_cvt_pk_bf16_f32 v104, v178, v179
	v_cvt_pk_bf16_f32 v105, v180, v181
	s_waitcnt lgkmcnt(0)
	v_cvt_pk_bf16_f32 v106, v182, v183
	v_cvt_pk_bf16_f32 v107, v184, v185
	v_cvt_pk_bf16_f32 v108, v186, v187
	v_cvt_pk_bf16_f32 v109, v188, v189
	global_store_dwordx4 v74, v[94:97], s[38:39]
	global_store_dwordx4 v75, v[98:101], s[38:39]
	global_store_dwordx4 v76, v[102:105], s[38:39]
	global_store_dwordx4 v77, v[106:109], s[38:39]
	s_lshr_b32 s34, s30, 6
	s_and_b32 s35, s30, 63
	s_mov_b32 s45, s30
	s_lshl_b32 s36, s34, 19
	s_lshl_b32 s37, s35, 7
	s_add_i32 s36, s36, s37
	s_add_u32 s38, s26, s36
	s_addc_u32 s39, s27, 0
	global_load_dwordx4 v[158:161], v4, s[38:39] nt
	s_add_u32 s38, s38, 0x10000
	s_addc_u32 s39, s39, 0
	global_load_dwordx4 v[162:165], v4, s[38:39] nt
	s_add_u32 s38, s38, 0x10000
	s_addc_u32 s39, s39, 0
	global_load_dwordx4 v[166:169], v4, s[38:39] nt
	s_add_u32 s38, s38, 0x10000
	s_addc_u32 s39, s39, 0
	global_load_dwordx4 v[170:173], v4, s[38:39] nt
	s_add_u32 s38, s38, 0x10000
	s_addc_u32 s39, s39, 0
	global_load_dwordx4 v[174:177], v4, s[38:39] nt
	s_add_u32 s38, s38, 0x10000
	s_addc_u32 s39, s39, 0
	global_load_dwordx4 v[178:181], v4, s[38:39] nt
	s_add_u32 s38, s38, 0x10000
	s_addc_u32 s39, s39, 0
	global_load_dwordx4 v[182:185], v4, s[38:39] nt
	s_add_u32 s38, s38, 0x10000
	s_addc_u32 s39, s39, 0
	global_load_dwordx4 v[186:189], v4, s[38:39] nt
	s_addk_i32 s30, 0x180
	s_and_b32 s30, s30, 0x7ff
	s_waitcnt vmcnt(36)
	ds_write_b128 v110, v[10:13]
	ds_write_b128 v111, v[14:17] offset:1024
	ds_write_b128 v112, v[18:21] offset:2048
	ds_write_b128 v113, v[22:25] offset:3072
	ds_write_b128 v114, v[26:29] offset:4096
	ds_write_b128 v115, v[30:33] offset:5120
	ds_write_b128 v116, v[34:37] offset:6144
	ds_write_b128 v117, v[38:41] offset:7168
	ds_read2_b32 v[10:11], v118 offset1:32
	ds_read2_b32 v[12:13], v118 offset0:64 offset1:96
	ds_read2_b32 v[14:15], v118 offset0:128 offset1:160
	ds_read2_b32 v[16:17], v118 offset0:192 offset1:224
	ds_read2_b32 v[18:19], v119 offset1:32
	ds_read2_b32 v[20:21], v119 offset0:64 offset1:96
	ds_read2_b32 v[22:23], v119 offset0:128 offset1:160
	ds_read2_b32 v[24:25], v119 offset0:192 offset1:224
	ds_read2_b32 v[26:27], v120 offset1:32
	ds_read2_b32 v[28:29], v120 offset0:64 offset1:96
	ds_read2_b32 v[30:31], v120 offset0:128 offset1:160
	ds_read2_b32 v[32:33], v120 offset0:192 offset1:224
	ds_read2_b32 v[34:35], v121 offset1:32
	ds_read2_b32 v[36:37], v121 offset0:64 offset1:96
	ds_read2_b32 v[38:39], v121 offset0:128 offset1:160
	ds_read2_b32 v[40:41], v121 offset0:192 offset1:224
	s_lshr_b32 s34, s40, 6
	s_and_b32 s35, s40, 63
	s_lshl_b32 s36, s35, 17
	s_lshl_b32 s37, s34, 7
	s_add_i32 s36, s36, s37
	s_add_u32 s38, s28, s36
	s_addc_u32 s39, s29, 0
	s_waitcnt lgkmcnt(12)
	v_cvt_pk_bf16_f32 v78, v10, v11
	v_cvt_pk_bf16_f32 v79, v12, v13
	v_cvt_pk_bf16_f32 v80, v14, v15
	v_cvt_pk_bf16_f32 v81, v16, v17
	s_waitcnt lgkmcnt(8)
	v_cvt_pk_bf16_f32 v82, v18, v19
	v_cvt_pk_bf16_f32 v83, v20, v21
	v_cvt_pk_bf16_f32 v84, v22, v23
	v_cvt_pk_bf16_f32 v85, v24, v25
	s_waitcnt lgkmcnt(4)
	v_cvt_pk_bf16_f32 v86, v26, v27
	v_cvt_pk_bf16_f32 v87, v28, v29
	v_cvt_pk_bf16_f32 v88, v30, v31
	v_cvt_pk_bf16_f32 v89, v32, v33
	s_waitcnt lgkmcnt(0)
	v_cvt_pk_bf16_f32 v90, v34, v35
	v_cvt_pk_bf16_f32 v91, v36, v37
	v_cvt_pk_bf16_f32 v92, v38, v39
	v_cvt_pk_bf16_f32 v93, v40, v41
	global_store_dwordx4 v74, v[78:81], s[38:39]
	global_store_dwordx4 v75, v[82:85], s[38:39]
	global_store_dwordx4 v76, v[86:89], s[38:39]
	global_store_dwordx4 v77, v[90:93], s[38:39]
	s_waitcnt vmcnt(28)
	ds_write_b128 v110, v[42:45]
	ds_write_b128 v111, v[46:49] offset:1024
	ds_write_b128 v112, v[50:53] offset:2048
	ds_write_b128 v113, v[54:57] offset:3072
	ds_write_b128 v114, v[58:61] offset:4096
	ds_write_b128 v115, v[62:65] offset:5120
	ds_write_b128 v116, v[66:69] offset:6144
	ds_write_b128 v117, v[70:73] offset:7168
	ds_read2_b32 v[42:43], v118 offset1:32
	ds_read2_b32 v[44:45], v118 offset0:64 offset1:96
	ds_read2_b32 v[46:47], v118 offset0:128 offset1:160
	ds_read2_b32 v[48:49], v118 offset0:192 offset1:224
	ds_read2_b32 v[50:51], v119 offset1:32
	ds_read2_b32 v[52:53], v119 offset0:64 offset1:96
	ds_read2_b32 v[54:55], v119 offset0:128 offset1:160
	ds_read2_b32 v[56:57], v119 offset0:192 offset1:224
	ds_read2_b32 v[58:59], v120 offset1:32
	ds_read2_b32 v[60:61], v120 offset0:64 offset1:96
	ds_read2_b32 v[62:63], v120 offset0:128 offset1:160
	ds_read2_b32 v[64:65], v120 offset0:192 offset1:224
	ds_read2_b32 v[66:67], v121 offset1:32
	ds_read2_b32 v[68:69], v121 offset0:64 offset1:96
	ds_read2_b32 v[70:71], v121 offset0:128 offset1:160
	ds_read2_b32 v[72:73], v121 offset0:192 offset1:224
	s_lshr_b32 s34, s41, 6
	s_and_b32 s35, s41, 63
	s_lshl_b32 s36, s35, 17
	s_lshl_b32 s37, s34, 7
	s_add_i32 s36, s36, s37
	s_add_u32 s38, s28, s36
	s_addc_u32 s39, s29, 0
	s_waitcnt lgkmcnt(12)
	v_cvt_pk_bf16_f32 v94, v42, v43
	v_cvt_pk_bf16_f32 v95, v44, v45
	v_cvt_pk_bf16_f32 v96, v46, v47
	v_cvt_pk_bf16_f32 v97, v48, v49
	s_waitcnt lgkmcnt(8)
	v_cvt_pk_bf16_f32 v98, v50, v51
	v_cvt_pk_bf16_f32 v99, v52, v53
	v_cvt_pk_bf16_f32 v100, v54, v55
	v_cvt_pk_bf16_f32 v101, v56, v57
	s_waitcnt lgkmcnt(4)
	v_cvt_pk_bf16_f32 v102, v58, v59
	v_cvt_pk_bf16_f32 v103, v60, v61
	v_cvt_pk_bf16_f32 v104, v62, v63
	v_cvt_pk_bf16_f32 v105, v64, v65
	s_waitcnt lgkmcnt(0)
	v_cvt_pk_bf16_f32 v106, v66, v67
	v_cvt_pk_bf16_f32 v107, v68, v69
	v_cvt_pk_bf16_f32 v108, v70, v71
	v_cvt_pk_bf16_f32 v109, v72, v73
	global_store_dwordx4 v74, v[94:97], s[38:39]
	global_store_dwordx4 v75, v[98:101], s[38:39]
	global_store_dwordx4 v76, v[102:105], s[38:39]
	global_store_dwordx4 v77, v[106:109], s[38:39]
	s_waitcnt vmcnt(20)
	ds_write_b128 v110, v[126:129]
	ds_write_b128 v111, v[130:133] offset:1024
	ds_write_b128 v112, v[134:137] offset:2048
	ds_write_b128 v113, v[138:141] offset:3072
	ds_write_b128 v114, v[142:145] offset:4096
	ds_write_b128 v115, v[146:149] offset:5120
	ds_write_b128 v116, v[150:153] offset:6144
	ds_write_b128 v117, v[154:157] offset:7168
	ds_read2_b32 v[126:127], v118 offset1:32
	ds_read2_b32 v[128:129], v118 offset0:64 offset1:96
	ds_read2_b32 v[130:131], v118 offset0:128 offset1:160
	ds_read2_b32 v[132:133], v118 offset0:192 offset1:224
	ds_read2_b32 v[134:135], v119 offset1:32
	ds_read2_b32 v[136:137], v119 offset0:64 offset1:96
	ds_read2_b32 v[138:139], v119 offset0:128 offset1:160
	ds_read2_b32 v[140:141], v119 offset0:192 offset1:224
	ds_read2_b32 v[142:143], v120 offset1:32
	ds_read2_b32 v[144:145], v120 offset0:64 offset1:96
	ds_read2_b32 v[146:147], v120 offset0:128 offset1:160
	ds_read2_b32 v[148:149], v120 offset0:192 offset1:224
	ds_read2_b32 v[150:151], v121 offset1:32
	ds_read2_b32 v[152:153], v121 offset0:64 offset1:96
	ds_read2_b32 v[154:155], v121 offset0:128 offset1:160
	ds_read2_b32 v[156:157], v121 offset0:192 offset1:224
	s_lshr_b32 s34, s44, 6
	s_and_b32 s35, s44, 63
	s_lshl_b32 s36, s35, 17
	s_lshl_b32 s37, s34, 7
	s_add_i32 s36, s36, s37
	s_add_u32 s38, s28, s36
	s_addc_u32 s39, s29, 0
	s_waitcnt lgkmcnt(12)
	v_cvt_pk_bf16_f32 v78, v126, v127
	v_cvt_pk_bf16_f32 v79, v128, v129
	v_cvt_pk_bf16_f32 v80, v130, v131
	v_cvt_pk_bf16_f32 v81, v132, v133
	s_waitcnt lgkmcnt(8)
	v_cvt_pk_bf16_f32 v82, v134, v135
	v_cvt_pk_bf16_f32 v83, v136, v137
	v_cvt_pk_bf16_f32 v84, v138, v139
	v_cvt_pk_bf16_f32 v85, v140, v141
	s_waitcnt lgkmcnt(4)
	v_cvt_pk_bf16_f32 v86, v142, v143
	v_cvt_pk_bf16_f32 v87, v144, v145
	v_cvt_pk_bf16_f32 v88, v146, v147
	v_cvt_pk_bf16_f32 v89, v148, v149
	s_waitcnt lgkmcnt(0)
	v_cvt_pk_bf16_f32 v90, v150, v151
	v_cvt_pk_bf16_f32 v91, v152, v153
	v_cvt_pk_bf16_f32 v92, v154, v155
	v_cvt_pk_bf16_f32 v93, v156, v157
	global_store_dwordx4 v74, v[78:81], s[38:39]
	global_store_dwordx4 v75, v[82:85], s[38:39]
	global_store_dwordx4 v76, v[86:89], s[38:39]
	global_store_dwordx4 v77, v[90:93], s[38:39]
	s_waitcnt vmcnt(12)
	ds_write_b128 v110, v[158:161]
	ds_write_b128 v111, v[162:165] offset:1024
	ds_write_b128 v112, v[166:169] offset:2048
	ds_write_b128 v113, v[170:173] offset:3072
	ds_write_b128 v114, v[174:177] offset:4096
	ds_write_b128 v115, v[178:181] offset:5120
	ds_write_b128 v116, v[182:185] offset:6144
	ds_write_b128 v117, v[186:189] offset:7168
	ds_read2_b32 v[158:159], v118 offset1:32
	ds_read2_b32 v[160:161], v118 offset0:64 offset1:96
	ds_read2_b32 v[162:163], v118 offset0:128 offset1:160
	ds_read2_b32 v[164:165], v118 offset0:192 offset1:224
	ds_read2_b32 v[166:167], v119 offset1:32
	ds_read2_b32 v[168:169], v119 offset0:64 offset1:96
	ds_read2_b32 v[170:171], v119 offset0:128 offset1:160
	ds_read2_b32 v[172:173], v119 offset0:192 offset1:224
	ds_read2_b32 v[174:175], v120 offset1:32
	ds_read2_b32 v[176:177], v120 offset0:64 offset1:96
	ds_read2_b32 v[178:179], v120 offset0:128 offset1:160
	ds_read2_b32 v[180:181], v120 offset0:192 offset1:224
	ds_read2_b32 v[182:183], v121 offset1:32
	ds_read2_b32 v[184:185], v121 offset0:64 offset1:96
	ds_read2_b32 v[186:187], v121 offset0:128 offset1:160
	ds_read2_b32 v[188:189], v121 offset0:192 offset1:224
	s_lshr_b32 s34, s45, 6
	s_and_b32 s35, s45, 63
	s_lshl_b32 s36, s35, 17
	s_lshl_b32 s37, s34, 7
	s_add_i32 s36, s36, s37
	s_add_u32 s38, s28, s36
	s_addc_u32 s39, s29, 0
	s_waitcnt lgkmcnt(12)
	v_cvt_pk_bf16_f32 v94, v158, v159
	v_cvt_pk_bf16_f32 v95, v160, v161
	v_cvt_pk_bf16_f32 v96, v162, v163
	v_cvt_pk_bf16_f32 v97, v164, v165
	s_waitcnt lgkmcnt(8)
	v_cvt_pk_bf16_f32 v98, v166, v167
	v_cvt_pk_bf16_f32 v99, v168, v169
	v_cvt_pk_bf16_f32 v100, v170, v171
	v_cvt_pk_bf16_f32 v101, v172, v173
	s_waitcnt lgkmcnt(4)
	v_cvt_pk_bf16_f32 v102, v174, v175
	v_cvt_pk_bf16_f32 v103, v176, v177
	v_cvt_pk_bf16_f32 v104, v178, v179
	v_cvt_pk_bf16_f32 v105, v180, v181
	s_waitcnt lgkmcnt(0)
	v_cvt_pk_bf16_f32 v106, v182, v183
	v_cvt_pk_bf16_f32 v107, v184, v185
	v_cvt_pk_bf16_f32 v108, v186, v187
	v_cvt_pk_bf16_f32 v109, v188, v189
	global_store_dwordx4 v74, v[94:97], s[38:39]
	global_store_dwordx4 v75, v[98:101], s[38:39]
	global_store_dwordx4 v76, v[102:105], s[38:39]
	global_store_dwordx4 v77, v[106:109], s[38:39]
	s_waitcnt vmcnt(0) lgkmcnt(0)
	s_branch .LBB0_1389
